# v15 + Gray-code MFMA walk over the whole 32-MFMA segment (both column blocks)
# baseline (speedup 1.0000x reference)
.LBB0_364:
	s_add_u32 s20, s18, 0xfff80080
	s_addc_u32 s21, s19, -1
	s_add_i32 s30, 0, 0x10000
	s_cmp_eq_u32 s29, 28
	s_cselect_b32 s23, s4, s21
	s_cselect_b32 s22, s24, s20
	s_cselect_b32 s21, s25, s28
	s_cselect_b32 s20, s26, s27
	s_add_i32 s42, 0, 0x14000
	v_add_u32_e32 v142, s30, v204
	v_add_u32_e32 v166, s42, v204
	ds_read_b128 v[130:133], v142
	ds_read_b128 v[134:137], v142 offset:1024
	ds_read_b128 v[138:141], v142 offset:2048
	ds_read_b128 v[142:145], v142 offset:3072
	ds_read_b128 v[146:149], v166
	ds_read_b128 v[150:153], v166 offset:1024
	ds_read_b128 v[154:157], v166 offset:2048
	ds_read_b128 v[166:169], v166 offset:3072
	v_lshl_add_u64 v[202:203], s[18:19], 0, v[162:163]
	s_add_i32 m0, s87, 0xc000
	ds_read_b128 v[170:173], v205
	ds_read_b128 v[174:177], v205 offset:1024
	ds_read_b128 v[178:181], v205 offset:2048
	ds_read_b128 v[182:185], v205 offset:3072
	ds_read_b128 v[186:189], v205 offset:4096
	ds_read_b128 v[190:193], v205 offset:5120
	ds_read_b128 v[206:209], v205 offset:6144
	ds_read_b128 v[210:213], v205 offset:7168
	global_load_lds_dwordx4 v[202:203], off
	v_lshl_add_u64 v[202:203], s[18:19], 0, v[164:165]
	s_add_i32 m0, s87, 0xe000
	s_nop 0
	global_load_lds_dwordx4 v[202:203], off
	s_waitcnt vmcnt(8)
	s_waitcnt lgkmcnt(0)
	s_setprio 1
	s_barrier
	v_mfma_f32_16x16x32_bf16 v[126:129], v[130:133], v[170:173], v[126:129]
	v_mfma_f32_16x16x32_bf16 v[126:129], v[134:137], v[174:177], v[126:129]
	v_mfma_f32_16x16x32_bf16 v[122:125], v[142:145], v[174:177], v[122:125]
	v_mfma_f32_16x16x32_bf16 v[122:125], v[138:141], v[170:173], v[122:125]
	v_mfma_f32_16x16x32_bf16 v[114:117], v[154:157], v[170:173], v[114:117]
	v_mfma_f32_16x16x32_bf16 v[114:117], v[166:169], v[174:177], v[114:117]
	v_mfma_f32_16x16x32_bf16 v[118:121], v[150:153], v[174:177], v[118:121]
	v_mfma_f32_16x16x32_bf16 v[118:121], v[146:149], v[170:173], v[118:121]
	v_mfma_f32_16x16x32_bf16 v[102:105], v[146:149], v[178:181], v[102:105]
	v_mfma_f32_16x16x32_bf16 v[102:105], v[150:153], v[182:185], v[102:105]
	v_mfma_f32_16x16x32_bf16 v[98:101], v[166:169], v[182:185], v[98:101]
	v_mfma_f32_16x16x32_bf16 v[98:101], v[154:157], v[178:181], v[98:101]
	v_mfma_f32_16x16x32_bf16 v[106:109], v[138:141], v[178:181], v[106:109]
	v_mfma_f32_16x16x32_bf16 v[106:109], v[142:145], v[182:185], v[106:109]
	v_mfma_f32_16x16x32_bf16 v[110:113], v[134:137], v[182:185], v[110:113]
	v_mfma_f32_16x16x32_bf16 v[110:113], v[130:133], v[178:181], v[110:113]
	v_mfma_f32_16x16x32_bf16 v[94:97], v[130:133], v[186:189], v[94:97]
	v_mfma_f32_16x16x32_bf16 v[94:97], v[134:137], v[190:193], v[94:97]
	v_mfma_f32_16x16x32_bf16 v[90:93], v[142:145], v[190:193], v[90:93]
	v_mfma_f32_16x16x32_bf16 v[90:93], v[138:141], v[186:189], v[90:93]
	v_mfma_f32_16x16x32_bf16 v[82:85], v[154:157], v[186:189], v[82:85]
	v_mfma_f32_16x16x32_bf16 v[82:85], v[166:169], v[190:193], v[82:85]
	v_mfma_f32_16x16x32_bf16 v[86:89], v[150:153], v[190:193], v[86:89]
	v_mfma_f32_16x16x32_bf16 v[86:89], v[146:149], v[186:189], v[86:89]
	v_mfma_f32_16x16x32_bf16 v[70:73], v[146:149], v[206:209], v[70:73]
	v_mfma_f32_16x16x32_bf16 v[70:73], v[150:153], v[210:213], v[70:73]
	v_mfma_f32_16x16x32_bf16 v[66:69], v[166:169], v[210:213], v[66:69]
	v_mfma_f32_16x16x32_bf16 v[66:69], v[154:157], v[206:209], v[66:69]
	v_mfma_f32_16x16x32_bf16 v[74:77], v[138:141], v[206:209], v[74:77]
	v_mfma_f32_16x16x32_bf16 v[74:77], v[142:145], v[210:213], v[74:77]
	v_mfma_f32_16x16x32_bf16 v[78:81], v[134:137], v[210:213], v[78:81]
	v_mfma_f32_16x16x32_bf16 v[78:81], v[130:133], v[206:209], v[78:81]
	s_barrier
	s_setprio 0
	s_add_i32 s30, s30, s39
	v_lshl_add_u64 v[202:203], s[20:21], 0, v[158:159]
	s_mov_b32 m0, s30
	ds_read_b128 v[170:173], v205 offset:16384
	ds_read_b128 v[174:177], v205 offset:17408
	ds_read_b128 v[178:181], v205 offset:18432
	ds_read_b128 v[182:185], v205 offset:19456
	ds_read_b128 v[186:189], v205 offset:20480
	ds_read_b128 v[190:193], v205 offset:21504
	ds_read_b128 v[206:209], v205 offset:22528
	ds_read_b128 v[210:213], v205 offset:23552
	global_load_lds_dwordx4 v[202:203], off
	s_add_i32 m0, s30, 0x2000
	s_add_u32 s30, s20, 0x80000
	v_lshl_add_u64 v[214:215], s[20:21], 0, v[160:161]
	s_addc_u32 s31, s21, 0
	s_add_i32 s42, s42, s39
	global_load_lds_dwordx4 v[214:215], off
	v_lshl_add_u64 v[216:217], s[30:31], 0, v[158:159]
	s_mov_b32 m0, s42
	v_lshl_add_u64 v[228:229], s[22:23], 0, v[160:161]
	global_load_lds_dwordx4 v[216:217], off
	v_lshl_add_u64 v[216:217], s[30:31], 0, v[160:161]
	s_add_i32 m0, s42, 0x2000
	s_nop 0
	global_load_lds_dwordx4 v[216:217], off
	v_lshl_add_u64 v[216:217], s[22:23], 0, v[158:159]
	s_mov_b32 m0, s87
	s_nop 0
	global_load_lds_dwordx4 v[216:217], off
	s_mov_b32 m0, s92
	s_nop 0
	global_load_lds_dwordx4 v[228:229], off
	s_waitcnt vmcnt(8)
	s_waitcnt lgkmcnt(0)
	s_setprio 1
	s_barrier
	v_mfma_f32_16x16x32_bf16 v[62:65], v[130:133], v[170:173], v[62:65]
	v_mfma_f32_16x16x32_bf16 v[62:65], v[134:137], v[174:177], v[62:65]
	v_mfma_f32_16x16x32_bf16 v[58:61], v[142:145], v[174:177], v[58:61]
	v_mfma_f32_16x16x32_bf16 v[58:61], v[138:141], v[170:173], v[58:61]
	v_mfma_f32_16x16x32_bf16 v[50:53], v[154:157], v[170:173], v[50:53]
	v_mfma_f32_16x16x32_bf16 v[50:53], v[166:169], v[174:177], v[50:53]
	v_mfma_f32_16x16x32_bf16 v[54:57], v[150:153], v[174:177], v[54:57]
	v_mfma_f32_16x16x32_bf16 v[54:57], v[146:149], v[170:173], v[54:57]
	v_mfma_f32_16x16x32_bf16 v[38:41], v[146:149], v[178:181], v[38:41]
	v_mfma_f32_16x16x32_bf16 v[38:41], v[150:153], v[182:185], v[38:41]
	v_mfma_f32_16x16x32_bf16 v[34:37], v[166:169], v[182:185], v[34:37]
	v_mfma_f32_16x16x32_bf16 v[34:37], v[154:157], v[178:181], v[34:37]
	v_mfma_f32_16x16x32_bf16 v[42:45], v[138:141], v[178:181], v[42:45]
	v_mfma_f32_16x16x32_bf16 v[42:45], v[142:145], v[182:185], v[42:45]
	v_mfma_f32_16x16x32_bf16 v[46:49], v[134:137], v[182:185], v[46:49]
	v_mfma_f32_16x16x32_bf16 v[46:49], v[130:133], v[178:181], v[46:49]
	v_mfma_f32_16x16x32_bf16 v[30:33], v[130:133], v[186:189], v[30:33]
	v_mfma_f32_16x16x32_bf16 v[30:33], v[134:137], v[190:193], v[30:33]
	v_mfma_f32_16x16x32_bf16 v[26:29], v[142:145], v[190:193], v[26:29]
	v_mfma_f32_16x16x32_bf16 v[26:29], v[138:141], v[186:189], v[26:29]
	v_mfma_f32_16x16x32_bf16 v[18:21], v[154:157], v[186:189], v[18:21]
	v_mfma_f32_16x16x32_bf16 v[18:21], v[166:169], v[190:193], v[18:21]
	v_mfma_f32_16x16x32_bf16 v[22:25], v[150:153], v[190:193], v[22:25]
	v_mfma_f32_16x16x32_bf16 v[22:25], v[146:149], v[186:189], v[22:25]
	v_mfma_f32_16x16x32_bf16 v[6:9], v[146:149], v[206:209], v[6:9]
	v_mfma_f32_16x16x32_bf16 v[6:9], v[150:153], v[210:213], v[6:9]
	v_mfma_f32_16x16x32_bf16 v[2:5], v[166:169], v[210:213], v[2:5]
	v_mfma_f32_16x16x32_bf16 v[2:5], v[154:157], v[206:209], v[2:5]
	v_mfma_f32_16x16x32_bf16 v[10:13], v[138:141], v[206:209], v[10:13]
	v_mfma_f32_16x16x32_bf16 v[10:13], v[142:145], v[210:213], v[10:13]
	v_mfma_f32_16x16x32_bf16 v[14:17], v[134:137], v[210:213], v[14:17]
	v_mfma_f32_16x16x32_bf16 v[14:17], v[130:133], v[206:209], v[14:17]
	s_barrier
	s_setprio 0
	s_add_i32 s30, 0, 0x18000
	s_add_i32 s31, 0, 0x1c000
	v_add_u32_e32 v142, s30, v204
	v_add_u32_e32 v166, s31, v204
	ds_read_b128 v[130:133], v142
	ds_read_b128 v[134:137], v142 offset:1024
	ds_read_b128 v[138:141], v142 offset:2048
	ds_read_b128 v[142:145], v142 offset:3072
	ds_read_b128 v[146:149], v166
	ds_read_b128 v[150:153], v166 offset:1024
	ds_read_b128 v[154:157], v166 offset:2048
	ds_read_b128 v[166:169], v166 offset:3072
	s_add_u32 s22, s22, 0x80000
	s_addc_u32 s23, s23, 0
	s_mov_b32 m0, s8
	v_lshl_add_u64 v[230:231], s[22:23], 0, v[158:159]
	ds_read_b128 v[170:173], v205 offset:32768
	ds_read_b128 v[174:177], v205 offset:33792
	ds_read_b128 v[178:181], v205 offset:34816
	ds_read_b128 v[182:185], v205 offset:35840
	ds_read_b128 v[186:189], v205 offset:36864
	ds_read_b128 v[190:193], v205 offset:37888
	ds_read_b128 v[206:209], v205 offset:38912
	ds_read_b128 v[210:213], v205 offset:39936
	global_load_lds_dwordx4 v[230:231], off
	v_lshl_add_u64 v[230:231], s[22:23], 0, v[160:161]
	s_mov_b32 m0, s9
	s_nop 0
	global_load_lds_dwordx4 v[230:231], off
	s_waitcnt vmcnt(8)
	s_waitcnt lgkmcnt(0)
	s_setprio 1
	s_barrier
	v_mfma_f32_16x16x32_bf16 v[126:129], v[130:133], v[170:173], v[126:129]
	v_mfma_f32_16x16x32_bf16 v[126:129], v[134:137], v[174:177], v[126:129]
	v_mfma_f32_16x16x32_bf16 v[122:125], v[142:145], v[174:177], v[122:125]
	v_mfma_f32_16x16x32_bf16 v[122:125], v[138:141], v[170:173], v[122:125]
	v_mfma_f32_16x16x32_bf16 v[114:117], v[154:157], v[170:173], v[114:117]
	v_mfma_f32_16x16x32_bf16 v[114:117], v[166:169], v[174:177], v[114:117]
	v_mfma_f32_16x16x32_bf16 v[118:121], v[150:153], v[174:177], v[118:121]
	v_mfma_f32_16x16x32_bf16 v[118:121], v[146:149], v[170:173], v[118:121]
	v_mfma_f32_16x16x32_bf16 v[102:105], v[146:149], v[178:181], v[102:105]
	v_mfma_f32_16x16x32_bf16 v[102:105], v[150:153], v[182:185], v[102:105]
	v_mfma_f32_16x16x32_bf16 v[98:101], v[166:169], v[182:185], v[98:101]
	v_mfma_f32_16x16x32_bf16 v[98:101], v[154:157], v[178:181], v[98:101]
	v_mfma_f32_16x16x32_bf16 v[106:109], v[138:141], v[178:181], v[106:109]
	v_mfma_f32_16x16x32_bf16 v[106:109], v[142:145], v[182:185], v[106:109]
	v_mfma_f32_16x16x32_bf16 v[110:113], v[134:137], v[182:185], v[110:113]
	v_mfma_f32_16x16x32_bf16 v[110:113], v[130:133], v[178:181], v[110:113]
	v_mfma_f32_16x16x32_bf16 v[94:97], v[130:133], v[186:189], v[94:97]
	v_mfma_f32_16x16x32_bf16 v[94:97], v[134:137], v[190:193], v[94:97]
	v_mfma_f32_16x16x32_bf16 v[90:93], v[142:145], v[190:193], v[90:93]
	v_mfma_f32_16x16x32_bf16 v[90:93], v[138:141], v[186:189], v[90:93]
	v_mfma_f32_16x16x32_bf16 v[82:85], v[154:157], v[186:189], v[82:85]
	v_mfma_f32_16x16x32_bf16 v[82:85], v[166:169], v[190:193], v[82:85]
	v_mfma_f32_16x16x32_bf16 v[86:89], v[150:153], v[190:193], v[86:89]
	v_mfma_f32_16x16x32_bf16 v[86:89], v[146:149], v[186:189], v[86:89]
	v_mfma_f32_16x16x32_bf16 v[70:73], v[146:149], v[206:209], v[70:73]
	v_mfma_f32_16x16x32_bf16 v[70:73], v[150:153], v[210:213], v[70:73]
	v_mfma_f32_16x16x32_bf16 v[66:69], v[166:169], v[210:213], v[66:69]
	v_mfma_f32_16x16x32_bf16 v[66:69], v[154:157], v[206:209], v[66:69]
	v_mfma_f32_16x16x32_bf16 v[74:77], v[138:141], v[206:209], v[74:77]
	v_mfma_f32_16x16x32_bf16 v[74:77], v[142:145], v[210:213], v[74:77]
	v_mfma_f32_16x16x32_bf16 v[78:81], v[134:137], v[210:213], v[78:81]
	v_mfma_f32_16x16x32_bf16 v[78:81], v[130:133], v[206:209], v[78:81]
	s_barrier
	s_setprio 0
	s_add_i32 s22, s30, s39
	v_lshl_add_u64 v[202:203], v[202:203], 0, s[10:11]
	s_mov_b32 m0, s22
	ds_read_b128 v[170:173], v205 offset:49152
	ds_read_b128 v[174:177], v205 offset:50176
	ds_read_b128 v[178:181], v205 offset:51200
	ds_read_b128 v[182:185], v205 offset:52224
	ds_read_b128 v[186:189], v205 offset:53248
	ds_read_b128 v[190:193], v205 offset:54272
	ds_read_b128 v[206:209], v205 offset:55296
	ds_read_b128 v[210:213], v205 offset:56320
	global_load_lds_dwordx4 v[202:203], off
	s_add_i32 m0, s22, 0x2000
	s_add_u32 s20, s20, 0x80080
	v_lshl_add_u64 v[202:203], v[214:215], 0, s[10:11]
	s_addc_u32 s21, s21, 0
	s_add_i32 s22, s31, s39
	global_load_lds_dwordx4 v[202:203], off
	v_lshl_add_u64 v[202:203], s[20:21], 0, v[158:159]
	s_mov_b32 m0, s22
	s_nop 0
	global_load_lds_dwordx4 v[202:203], off
	v_lshl_add_u64 v[202:203], s[20:21], 0, v[160:161]
	s_add_i32 m0, s22, 0x2000
	s_nop 0
	global_load_lds_dwordx4 v[202:203], off
	v_lshl_add_u64 v[202:203], v[216:217], 0, s[10:11]
	s_mov_b32 m0, s56
	s_nop 0
	global_load_lds_dwordx4 v[202:203], off
	v_lshl_add_u64 v[202:203], v[228:229], 0, s[10:11]
	s_mov_b32 m0, s57
	s_nop 0
	global_load_lds_dwordx4 v[202:203], off
	s_waitcnt vmcnt(8)
	s_waitcnt lgkmcnt(0)
	s_setprio 1
	s_barrier
	v_mfma_f32_16x16x32_bf16 v[62:65], v[130:133], v[170:173], v[62:65]
	v_mfma_f32_16x16x32_bf16 v[62:65], v[134:137], v[174:177], v[62:65]
	v_mfma_f32_16x16x32_bf16 v[58:61], v[142:145], v[174:177], v[58:61]
	v_mfma_f32_16x16x32_bf16 v[58:61], v[138:141], v[170:173], v[58:61]
	v_mfma_f32_16x16x32_bf16 v[50:53], v[154:157], v[170:173], v[50:53]
	v_mfma_f32_16x16x32_bf16 v[50:53], v[166:169], v[174:177], v[50:53]
	v_mfma_f32_16x16x32_bf16 v[54:57], v[150:153], v[174:177], v[54:57]
	v_mfma_f32_16x16x32_bf16 v[54:57], v[146:149], v[170:173], v[54:57]
	v_mfma_f32_16x16x32_bf16 v[38:41], v[146:149], v[178:181], v[38:41]
	v_mfma_f32_16x16x32_bf16 v[38:41], v[150:153], v[182:185], v[38:41]
	v_mfma_f32_16x16x32_bf16 v[34:37], v[166:169], v[182:185], v[34:37]
	v_mfma_f32_16x16x32_bf16 v[34:37], v[154:157], v[178:181], v[34:37]
	v_mfma_f32_16x16x32_bf16 v[42:45], v[138:141], v[178:181], v[42:45]
	v_mfma_f32_16x16x32_bf16 v[42:45], v[142:145], v[182:185], v[42:45]
	v_mfma_f32_16x16x32_bf16 v[46:49], v[134:137], v[182:185], v[46:49]
	v_mfma_f32_16x16x32_bf16 v[46:49], v[130:133], v[178:181], v[46:49]
	v_mfma_f32_16x16x32_bf16 v[30:33], v[130:133], v[186:189], v[30:33]
	v_mfma_f32_16x16x32_bf16 v[30:33], v[134:137], v[190:193], v[30:33]
	v_mfma_f32_16x16x32_bf16 v[26:29], v[142:145], v[190:193], v[26:29]
	v_mfma_f32_16x16x32_bf16 v[26:29], v[138:141], v[186:189], v[26:29]
	v_mfma_f32_16x16x32_bf16 v[18:21], v[154:157], v[186:189], v[18:21]
	v_mfma_f32_16x16x32_bf16 v[18:21], v[166:169], v[190:193], v[18:21]
	v_mfma_f32_16x16x32_bf16 v[22:25], v[150:153], v[190:193], v[22:25]
	v_mfma_f32_16x16x32_bf16 v[22:25], v[146:149], v[186:189], v[22:25]
	v_mfma_f32_16x16x32_bf16 v[6:9], v[146:149], v[206:209], v[6:9]
	v_mfma_f32_16x16x32_bf16 v[6:9], v[150:153], v[210:213], v[6:9]
	v_mfma_f32_16x16x32_bf16 v[2:5], v[166:169], v[210:213], v[2:5]
	v_mfma_f32_16x16x32_bf16 v[2:5], v[154:157], v[206:209], v[2:5]
	v_mfma_f32_16x16x32_bf16 v[10:13], v[138:141], v[206:209], v[10:13]
	v_mfma_f32_16x16x32_bf16 v[10:13], v[142:145], v[210:213], v[10:13]
	v_mfma_f32_16x16x32_bf16 v[14:17], v[134:137], v[210:213], v[14:17]
	v_mfma_f32_16x16x32_bf16 v[14:17], v[130:133], v[206:209], v[14:17]
	s_barrier
	s_setprio 0
	s_add_i32 s29, s29, 2
	s_add_u32 s18, s18, 0x100
	s_addc_u32 s19, s19, 0
	s_add_u32 s27, s27, 0x100
	s_addc_u32 s28, s28, 0
	s_cmp_gt_u32 s29, 29
	s_cbranch_scc0 .LBB0_364
	s_and_b64 vcc, exec, s[58:59]
	s_cbranch_vccz .LBB0_367
	s_barrier

.LBB0_986:
	s_add_u32 s24, s22, 0x100
	s_addc_u32 s25, s23, 0
	s_add_i32 s62, 0, 0x10000
	s_cmp_eq_u32 s61, 28
	s_cselect_b32 s29, s17, s25
	s_cselect_b32 s28, s58, s24
	v_add_u32_e32 v138, s62, v140
	s_cselect_b32 s27, s19, s60
	s_cselect_b32 s26, s18, s59
	s_add_i32 s63, 0, 0x14000
	ds_read_b128 v[142:145], v138
	ds_read_b128 v[146:149], v138 offset:1024
	ds_read_b128 v[150:153], v138 offset:2048
	ds_read_b128 v[154:157], v138 offset:3072
	v_add_u32_e32 v138, s63, v140
	ds_read_b128 v[158:161], v138
	ds_read_b128 v[162:165], v138 offset:1024
	ds_read_b128 v[166:169], v138 offset:2048
	ds_read_b128 v[170:173], v138 offset:3072
	v_lshl_add_u64 v[138:139], s[22:23], 0, v[134:135]
	s_add_i32 m0, s47, 0xc000
	ds_read_b128 v[174:177], v141
	ds_read_b128 v[178:181], v141 offset:1024
	ds_read_b128 v[182:185], v141 offset:2048
	ds_read_b128 v[186:189], v141 offset:3072
	ds_read_b128 v[190:193], v141 offset:4096
	ds_read_b128 v[202:205], v141 offset:5120
	ds_read_b128 v[206:209], v141 offset:6144
	ds_read_b128 v[210:213], v141 offset:7168
	global_load_lds_dwordx4 v[138:139], off
	v_lshl_add_u64 v[138:139], s[22:23], 0, v[136:137]
	s_add_i32 m0, s47, 0xe000
	s_nop 0
	global_load_lds_dwordx4 v[138:139], off
	s_waitcnt vmcnt(8)
	s_waitcnt lgkmcnt(0)
	s_setprio 1
	s_barrier
	v_mfma_f32_16x16x32_bf16 v[126:129], v[142:145], v[174:177], v[126:129]
	v_mfma_f32_16x16x32_bf16 v[126:129], v[146:149], v[178:181], v[126:129]
	v_mfma_f32_16x16x32_bf16 v[122:125], v[154:157], v[178:181], v[122:125]
	v_mfma_f32_16x16x32_bf16 v[122:125], v[150:153], v[174:177], v[122:125]
	v_mfma_f32_16x16x32_bf16 v[106:109], v[166:169], v[174:177], v[106:109]
	v_mfma_f32_16x16x32_bf16 v[106:109], v[170:173], v[178:181], v[106:109]
	v_mfma_f32_16x16x32_bf16 v[114:117], v[162:165], v[178:181], v[114:117]
	v_mfma_f32_16x16x32_bf16 v[114:117], v[158:161], v[174:177], v[114:117]
	v_mfma_f32_16x16x32_bf16 v[98:101], v[158:161], v[182:185], v[98:101]
	v_mfma_f32_16x16x32_bf16 v[98:101], v[162:165], v[186:189], v[98:101]
	v_mfma_f32_16x16x32_bf16 v[90:93], v[170:173], v[186:189], v[90:93]
	v_mfma_f32_16x16x32_bf16 v[90:93], v[166:169], v[182:185], v[90:93]
	v_mfma_f32_16x16x32_bf16 v[110:113], v[150:153], v[182:185], v[110:113]
	v_mfma_f32_16x16x32_bf16 v[110:113], v[154:157], v[186:189], v[110:113]
	v_mfma_f32_16x16x32_bf16 v[118:121], v[146:149], v[186:189], v[118:121]
	v_mfma_f32_16x16x32_bf16 v[118:121], v[142:145], v[182:185], v[118:121]
	v_mfma_f32_16x16x32_bf16 v[102:105], v[142:145], v[190:193], v[102:105]
	v_mfma_f32_16x16x32_bf16 v[102:105], v[146:149], v[202:205], v[102:105]
	v_mfma_f32_16x16x32_bf16 v[94:97], v[154:157], v[202:205], v[94:97]
	v_mfma_f32_16x16x32_bf16 v[94:97], v[150:153], v[190:193], v[94:97]
	v_mfma_f32_16x16x32_bf16 v[74:77], v[166:169], v[190:193], v[74:77]
	v_mfma_f32_16x16x32_bf16 v[74:77], v[170:173], v[202:205], v[74:77]
	v_mfma_f32_16x16x32_bf16 v[82:85], v[162:165], v[202:205], v[82:85]
	v_mfma_f32_16x16x32_bf16 v[82:85], v[158:161], v[190:193], v[82:85]
	v_mfma_f32_16x16x32_bf16 v[70:73], v[158:161], v[206:209], v[70:73]
	v_mfma_f32_16x16x32_bf16 v[70:73], v[162:165], v[210:213], v[70:73]
	v_mfma_f32_16x16x32_bf16 v[66:69], v[170:173], v[210:213], v[66:69]
	v_mfma_f32_16x16x32_bf16 v[66:69], v[166:169], v[206:209], v[66:69]
	v_mfma_f32_16x16x32_bf16 v[78:81], v[150:153], v[206:209], v[78:81]
	v_mfma_f32_16x16x32_bf16 v[78:81], v[154:157], v[210:213], v[78:81]
	v_mfma_f32_16x16x32_bf16 v[86:89], v[146:149], v[210:213], v[86:89]
	v_mfma_f32_16x16x32_bf16 v[86:89], v[142:145], v[206:209], v[86:89]
	s_barrier
	s_setprio 0
	s_add_i32 s22, s62, s36
	v_lshl_add_u64 v[138:139], s[26:27], 0, v[132:133]
	s_mov_b32 m0, s22
	ds_read_b128 v[174:177], v141 offset:16384
	ds_read_b128 v[178:181], v141 offset:17408
	ds_read_b128 v[182:185], v141 offset:18432
	ds_read_b128 v[186:189], v141 offset:19456
	ds_read_b128 v[190:193], v141 offset:20480
	ds_read_b128 v[202:205], v141 offset:21504
	ds_read_b128 v[206:209], v141 offset:22528
	ds_read_b128 v[210:213], v141 offset:23552
	global_load_lds_dwordx4 v[138:139], off
	s_add_i32 m0, s22, 0x2000
	s_add_u32 s22, s26, 0x80000
	v_lshl_add_u64 v[214:215], s[26:27], 0, v[130:131]
	s_addc_u32 s23, s27, 0
	s_add_i32 s62, s63, s36
	global_load_lds_dwordx4 v[214:215], off
	v_lshl_add_u64 v[216:217], s[22:23], 0, v[132:133]
	s_mov_b32 m0, s62
	v_lshl_add_u64 v[228:229], s[28:29], 0, v[130:131]
	global_load_lds_dwordx4 v[216:217], off
	v_lshl_add_u64 v[216:217], s[22:23], 0, v[130:131]
	s_add_i32 m0, s62, 0x2000
	s_nop 0
	global_load_lds_dwordx4 v[216:217], off
	v_lshl_add_u64 v[216:217], s[28:29], 0, v[132:133]
	s_mov_b32 m0, s47
	s_nop 0
	global_load_lds_dwordx4 v[216:217], off
	s_mov_b32 m0, s48
	s_nop 0
	global_load_lds_dwordx4 v[228:229], off
	s_waitcnt vmcnt(8)
	s_waitcnt lgkmcnt(0)
	s_setprio 1
	s_barrier
	v_mfma_f32_16x16x32_bf16 v[62:65], v[142:145], v[174:177], v[62:65]
	v_mfma_f32_16x16x32_bf16 v[62:65], v[146:149], v[178:181], v[62:65]
	v_mfma_f32_16x16x32_bf16 v[58:61], v[154:157], v[178:181], v[58:61]
	v_mfma_f32_16x16x32_bf16 v[58:61], v[150:153], v[174:177], v[58:61]
	v_mfma_f32_16x16x32_bf16 v[42:45], v[166:169], v[174:177], v[42:45]
	v_mfma_f32_16x16x32_bf16 v[42:45], v[170:173], v[178:181], v[42:45]
	v_mfma_f32_16x16x32_bf16 v[50:53], v[162:165], v[178:181], v[50:53]
	v_mfma_f32_16x16x32_bf16 v[50:53], v[158:161], v[174:177], v[50:53]
	v_mfma_f32_16x16x32_bf16 v[34:37], v[158:161], v[182:185], v[34:37]
	v_mfma_f32_16x16x32_bf16 v[34:37], v[162:165], v[186:189], v[34:37]
	v_mfma_f32_16x16x32_bf16 v[26:29], v[170:173], v[186:189], v[26:29]
	v_mfma_f32_16x16x32_bf16 v[26:29], v[166:169], v[182:185], v[26:29]
	v_mfma_f32_16x16x32_bf16 v[46:49], v[150:153], v[182:185], v[46:49]
	v_mfma_f32_16x16x32_bf16 v[46:49], v[154:157], v[186:189], v[46:49]
	v_mfma_f32_16x16x32_bf16 v[54:57], v[146:149], v[186:189], v[54:57]
	v_mfma_f32_16x16x32_bf16 v[54:57], v[142:145], v[182:185], v[54:57]
	v_mfma_f32_16x16x32_bf16 v[38:41], v[142:145], v[190:193], v[38:41]
	v_mfma_f32_16x16x32_bf16 v[38:41], v[146:149], v[202:205], v[38:41]
	v_mfma_f32_16x16x32_bf16 v[30:33], v[154:157], v[202:205], v[30:33]
	v_mfma_f32_16x16x32_bf16 v[30:33], v[150:153], v[190:193], v[30:33]
	v_mfma_f32_16x16x32_bf16 v[10:13], v[166:169], v[190:193], v[10:13]
	v_mfma_f32_16x16x32_bf16 v[10:13], v[170:173], v[202:205], v[10:13]
	v_mfma_f32_16x16x32_bf16 v[18:21], v[162:165], v[202:205], v[18:21]
	v_mfma_f32_16x16x32_bf16 v[18:21], v[158:161], v[190:193], v[18:21]
	v_mfma_f32_16x16x32_bf16 v[6:9], v[158:161], v[206:209], v[6:9]
	v_mfma_f32_16x16x32_bf16 v[6:9], v[162:165], v[210:213], v[6:9]
	v_mfma_f32_16x16x32_bf16 v[2:5], v[170:173], v[210:213], v[2:5]
	v_mfma_f32_16x16x32_bf16 v[2:5], v[166:169], v[206:209], v[2:5]
	v_mfma_f32_16x16x32_bf16 v[14:17], v[150:153], v[206:209], v[14:17]
	v_mfma_f32_16x16x32_bf16 v[14:17], v[154:157], v[210:213], v[14:17]
	v_mfma_f32_16x16x32_bf16 v[22:25], v[146:149], v[210:213], v[22:25]
	v_mfma_f32_16x16x32_bf16 v[22:25], v[142:145], v[206:209], v[22:25]
	s_barrier
	s_setprio 0
	s_add_i32 s62, 0, 0x18000
	s_add_i32 s63, 0, 0x1c000
	v_add_u32_e32 v154, s62, v140
	v_add_u32_e32 v170, s63, v140
	ds_read_b128 v[142:145], v154
	ds_read_b128 v[146:149], v154 offset:1024
	ds_read_b128 v[150:153], v154 offset:2048
	ds_read_b128 v[154:157], v154 offset:3072
	ds_read_b128 v[158:161], v170
	ds_read_b128 v[162:165], v170 offset:1024
	ds_read_b128 v[166:169], v170 offset:2048
	ds_read_b128 v[170:173], v170 offset:3072
	s_add_u32 s22, s28, 0x80000
	s_addc_u32 s23, s29, 0
	s_mov_b32 m0, s49
	v_lshl_add_u64 v[230:231], s[22:23], 0, v[132:133]
	ds_read_b128 v[174:177], v141 offset:32768
	ds_read_b128 v[178:181], v141 offset:33792
	ds_read_b128 v[182:185], v141 offset:34816
	ds_read_b128 v[186:189], v141 offset:35840
	ds_read_b128 v[190:193], v141 offset:36864
	ds_read_b128 v[202:205], v141 offset:37888
	ds_read_b128 v[206:209], v141 offset:38912
	ds_read_b128 v[210:213], v141 offset:39936
	global_load_lds_dwordx4 v[230:231], off
	v_lshl_add_u64 v[230:231], s[22:23], 0, v[130:131]
	s_mov_b32 m0, s50
	s_nop 0
	global_load_lds_dwordx4 v[230:231], off
	s_waitcnt vmcnt(8)
	s_waitcnt lgkmcnt(0)
	s_setprio 1
	s_barrier
	v_mfma_f32_16x16x32_bf16 v[126:129], v[142:145], v[174:177], v[126:129]
	v_mfma_f32_16x16x32_bf16 v[126:129], v[146:149], v[178:181], v[126:129]
	v_mfma_f32_16x16x32_bf16 v[122:125], v[154:157], v[178:181], v[122:125]
	v_mfma_f32_16x16x32_bf16 v[122:125], v[150:153], v[174:177], v[122:125]
	v_mfma_f32_16x16x32_bf16 v[106:109], v[166:169], v[174:177], v[106:109]
	v_mfma_f32_16x16x32_bf16 v[106:109], v[170:173], v[178:181], v[106:109]
	v_mfma_f32_16x16x32_bf16 v[114:117], v[162:165], v[178:181], v[114:117]
	v_mfma_f32_16x16x32_bf16 v[114:117], v[158:161], v[174:177], v[114:117]
	v_mfma_f32_16x16x32_bf16 v[98:101], v[158:161], v[182:185], v[98:101]
	v_mfma_f32_16x16x32_bf16 v[98:101], v[162:165], v[186:189], v[98:101]
	v_mfma_f32_16x16x32_bf16 v[90:93], v[170:173], v[186:189], v[90:93]
	v_mfma_f32_16x16x32_bf16 v[90:93], v[166:169], v[182:185], v[90:93]
	v_mfma_f32_16x16x32_bf16 v[110:113], v[150:153], v[182:185], v[110:113]
	v_mfma_f32_16x16x32_bf16 v[110:113], v[154:157], v[186:189], v[110:113]
	v_mfma_f32_16x16x32_bf16 v[118:121], v[146:149], v[186:189], v[118:121]
	v_mfma_f32_16x16x32_bf16 v[118:121], v[142:145], v[182:185], v[118:121]
	v_mfma_f32_16x16x32_bf16 v[102:105], v[142:145], v[190:193], v[102:105]
	v_mfma_f32_16x16x32_bf16 v[102:105], v[146:149], v[202:205], v[102:105]
	v_mfma_f32_16x16x32_bf16 v[94:97], v[154:157], v[202:205], v[94:97]
	v_mfma_f32_16x16x32_bf16 v[94:97], v[150:153], v[190:193], v[94:97]
	v_mfma_f32_16x16x32_bf16 v[74:77], v[166:169], v[190:193], v[74:77]
	v_mfma_f32_16x16x32_bf16 v[74:77], v[170:173], v[202:205], v[74:77]
	v_mfma_f32_16x16x32_bf16 v[82:85], v[162:165], v[202:205], v[82:85]
	v_mfma_f32_16x16x32_bf16 v[82:85], v[158:161], v[190:193], v[82:85]
	v_mfma_f32_16x16x32_bf16 v[70:73], v[158:161], v[206:209], v[70:73]
	v_mfma_f32_16x16x32_bf16 v[70:73], v[162:165], v[210:213], v[70:73]
	v_mfma_f32_16x16x32_bf16 v[66:69], v[170:173], v[210:213], v[66:69]
	v_mfma_f32_16x16x32_bf16 v[66:69], v[166:169], v[206:209], v[66:69]
	v_mfma_f32_16x16x32_bf16 v[78:81], v[150:153], v[206:209], v[78:81]
	v_mfma_f32_16x16x32_bf16 v[78:81], v[154:157], v[210:213], v[78:81]
	v_mfma_f32_16x16x32_bf16 v[86:89], v[146:149], v[210:213], v[86:89]
	v_mfma_f32_16x16x32_bf16 v[86:89], v[142:145], v[206:209], v[86:89]
	s_barrier
	s_setprio 0
	s_add_i32 s22, s62, s36
	v_lshl_add_u64 v[138:139], v[138:139], 0, s[10:11]
	s_mov_b32 m0, s22
	ds_read_b128 v[174:177], v141 offset:49152
	ds_read_b128 v[178:181], v141 offset:50176
	ds_read_b128 v[182:185], v141 offset:51200
	ds_read_b128 v[186:189], v141 offset:52224
	ds_read_b128 v[190:193], v141 offset:53248
	ds_read_b128 v[202:205], v141 offset:54272
	ds_read_b128 v[206:209], v141 offset:55296
	ds_read_b128 v[210:213], v141 offset:56320
	global_load_lds_dwordx4 v[138:139], off
	s_add_i32 m0, s22, 0x2000
	s_add_u32 s22, s26, 0x80080
	v_lshl_add_u64 v[138:139], v[214:215], 0, s[10:11]
	s_addc_u32 s23, s27, 0
	s_add_i32 s26, s63, s36
	global_load_lds_dwordx4 v[138:139], off
	v_lshl_add_u64 v[138:139], s[22:23], 0, v[132:133]
	s_mov_b32 m0, s26
	s_nop 0
	global_load_lds_dwordx4 v[138:139], off
	v_lshl_add_u64 v[138:139], s[22:23], 0, v[130:131]
	s_add_i32 m0, s26, 0x2000
	s_nop 0
	global_load_lds_dwordx4 v[138:139], off
	v_lshl_add_u64 v[138:139], v[216:217], 0, s[10:11]
	s_mov_b32 m0, s51
	s_nop 0
	global_load_lds_dwordx4 v[138:139], off
	v_lshl_add_u64 v[138:139], v[228:229], 0, s[10:11]
	s_mov_b32 m0, s52
	s_nop 0
	global_load_lds_dwordx4 v[138:139], off
	s_waitcnt vmcnt(8)
	s_waitcnt lgkmcnt(0)
	s_setprio 1
	s_barrier
	v_mfma_f32_16x16x32_bf16 v[62:65], v[142:145], v[174:177], v[62:65]
	v_mfma_f32_16x16x32_bf16 v[62:65], v[146:149], v[178:181], v[62:65]
	v_mfma_f32_16x16x32_bf16 v[58:61], v[154:157], v[178:181], v[58:61]
	v_mfma_f32_16x16x32_bf16 v[58:61], v[150:153], v[174:177], v[58:61]
	v_mfma_f32_16x16x32_bf16 v[42:45], v[166:169], v[174:177], v[42:45]
	v_mfma_f32_16x16x32_bf16 v[42:45], v[170:173], v[178:181], v[42:45]
	v_mfma_f32_16x16x32_bf16 v[50:53], v[162:165], v[178:181], v[50:53]
	v_mfma_f32_16x16x32_bf16 v[50:53], v[158:161], v[174:177], v[50:53]
	v_mfma_f32_16x16x32_bf16 v[34:37], v[158:161], v[182:185], v[34:37]
	v_mfma_f32_16x16x32_bf16 v[34:37], v[162:165], v[186:189], v[34:37]
	v_mfma_f32_16x16x32_bf16 v[26:29], v[170:173], v[186:189], v[26:29]
	v_mfma_f32_16x16x32_bf16 v[26:29], v[166:169], v[182:185], v[26:29]
	v_mfma_f32_16x16x32_bf16 v[46:49], v[150:153], v[182:185], v[46:49]
	v_mfma_f32_16x16x32_bf16 v[46:49], v[154:157], v[186:189], v[46:49]
	v_mfma_f32_16x16x32_bf16 v[54:57], v[146:149], v[186:189], v[54:57]
	v_mfma_f32_16x16x32_bf16 v[54:57], v[142:145], v[182:185], v[54:57]
	v_mfma_f32_16x16x32_bf16 v[38:41], v[142:145], v[190:193], v[38:41]
	v_mfma_f32_16x16x32_bf16 v[38:41], v[146:149], v[202:205], v[38:41]
	v_mfma_f32_16x16x32_bf16 v[30:33], v[154:157], v[202:205], v[30:33]
	v_mfma_f32_16x16x32_bf16 v[30:33], v[150:153], v[190:193], v[30:33]
	v_mfma_f32_16x16x32_bf16 v[10:13], v[166:169], v[190:193], v[10:13]
	v_mfma_f32_16x16x32_bf16 v[10:13], v[170:173], v[202:205], v[10:13]
	v_mfma_f32_16x16x32_bf16 v[18:21], v[162:165], v[202:205], v[18:21]
	v_mfma_f32_16x16x32_bf16 v[18:21], v[158:161], v[190:193], v[18:21]
	v_mfma_f32_16x16x32_bf16 v[6:9], v[158:161], v[206:209], v[6:9]
	v_mfma_f32_16x16x32_bf16 v[6:9], v[162:165], v[210:213], v[6:9]
	v_mfma_f32_16x16x32_bf16 v[2:5], v[170:173], v[210:213], v[2:5]
	v_mfma_f32_16x16x32_bf16 v[2:5], v[166:169], v[206:209], v[2:5]
	v_mfma_f32_16x16x32_bf16 v[14:17], v[150:153], v[206:209], v[14:17]
	v_mfma_f32_16x16x32_bf16 v[14:17], v[154:157], v[210:213], v[14:17]
	v_mfma_f32_16x16x32_bf16 v[22:25], v[146:149], v[210:213], v[22:25]
	v_mfma_f32_16x16x32_bf16 v[22:25], v[142:145], v[206:209], v[22:25]
	s_barrier
	s_setprio 0
	s_add_i32 s61, s61, 2
	s_add_u32 s59, s59, 0x100
	s_addc_u32 s60, s60, 0
	s_cmp_gt_u32 s61, 29
	s_mov_b64 s[22:23], s[24:25]
	s_cbranch_scc0 .LBB0_986
	s_and_b64 vcc, exec, s[14:15]
	s_cbranch_vccz .LBB0_989
	s_barrier

.LBB0_1002:
	s_add_i32 s36, s21, 0x100
	s_and_b64 s[30:31], s[28:29], exec
	s_cselect_b32 s31, 0, s36
	s_cselect_b32 s30, 0, 0
	s_add_u32 s36, s8, s31
	s_addc_u32 s37, s9, s30
	s_add_u32 s30, s24, s21
	s_addc_u32 s31, s25, 0
	s_add_u32 s30, s30, 0x100
	s_addc_u32 s31, s31, 0
	s_add_i32 s71, 0, 0x10000
	s_and_b64 s[28:29], s[28:29], exec
	s_cselect_b32 s39, s19, s31
	s_cselect_b32 s38, s18, s30
	s_add_i32 s29, 0, 0x14000
	s_add_u32 s21, s44, s21
	s_addc_u32 s28, s45, 0
	s_add_u32 s48, s21, 0x17110080
	s_addc_u32 s49, s28, 0
	s_add_i32 s70, s71, s52
	s_add_i32 m0, s53, 0xc000
	s_add_i32 s73, s53, 0xe000
	s_add_i32 s67, s70, 0x2000
	v_add_u32_e32 v134, s71, v136
	s_add_u32 s46, s38, 0x10000
	ds_read_b128 v[138:141], v134
	ds_read_b128 v[142:145], v134 offset:1024
	ds_read_b128 v[146:149], v134 offset:2048
	ds_read_b128 v[150:153], v134 offset:3072
	v_add_u32_e32 v134, s29, v136
	s_addc_u32 s47, s39, 0
	s_add_i32 s69, s29, s52
	ds_read_b128 v[154:157], v134
	ds_read_b128 v[158:161], v134 offset:1024
	ds_read_b128 v[162:165], v134 offset:2048
	ds_read_b128 v[166:169], v134 offset:3072
	s_add_i32 s68, s69, 0x2000
	s_add_i32 s66, 0, 0x18000
	s_add_i32 s65, 0, 0x1c000
	s_add_u32 s30, s36, 0x10000
	s_addc_u32 s31, s37, 0
	s_add_i32 s64, s66, s52
	s_add_i32 s21, s64, 0x2000
	s_add_u32 s28, s38, 0x10080
	s_addc_u32 s29, s39, 0
	s_add_i32 s72, s65, s52
	s_add_i32 s71, s72, 0x2000
	v_lshl_add_u64 v[134:135], s[48:49], 0, v[132:133]
	ds_read_b128 v[170:173], v137
	ds_read_b128 v[174:177], v137 offset:1024
	ds_read_b128 v[178:181], v137 offset:2048
	ds_read_b128 v[182:185], v137 offset:3072
	ds_read_b128 v[186:189], v137 offset:4096
	ds_read_b128 v[190:193], v137 offset:5120
	ds_read_b128 v[202:205], v137 offset:6144
	ds_read_b128 v[206:209], v137 offset:7168
	global_load_lds_dwordx4 v[134:135], off
	v_lshl_add_u64 v[134:135], s[48:49], 0, v[130:131]
	s_mov_b32 m0, s73
	s_nop 0
	global_load_lds_dwordx4 v[134:135], off
	s_waitcnt vmcnt(8)
	s_waitcnt lgkmcnt(0)
	s_setprio 1
	s_barrier
	v_mfma_f32_16x16x32_bf16 v[126:129], v[138:141], v[170:173], v[126:129]
	v_mfma_f32_16x16x32_bf16 v[126:129], v[142:145], v[174:177], v[126:129]
	v_mfma_f32_16x16x32_bf16 v[122:125], v[150:153], v[174:177], v[122:125]
	v_mfma_f32_16x16x32_bf16 v[122:125], v[146:149], v[170:173], v[122:125]
	v_mfma_f32_16x16x32_bf16 v[106:109], v[162:165], v[170:173], v[106:109]
	v_mfma_f32_16x16x32_bf16 v[106:109], v[166:169], v[174:177], v[106:109]
	v_mfma_f32_16x16x32_bf16 v[114:117], v[158:161], v[174:177], v[114:117]
	v_mfma_f32_16x16x32_bf16 v[114:117], v[154:157], v[170:173], v[114:117]
	v_mfma_f32_16x16x32_bf16 v[98:101], v[154:157], v[178:181], v[98:101]
	v_mfma_f32_16x16x32_bf16 v[98:101], v[158:161], v[182:185], v[98:101]
	v_mfma_f32_16x16x32_bf16 v[90:93], v[166:169], v[182:185], v[90:93]
	v_mfma_f32_16x16x32_bf16 v[90:93], v[162:165], v[178:181], v[90:93]
	v_mfma_f32_16x16x32_bf16 v[110:113], v[146:149], v[178:181], v[110:113]
	v_mfma_f32_16x16x32_bf16 v[110:113], v[150:153], v[182:185], v[110:113]
	v_mfma_f32_16x16x32_bf16 v[118:121], v[142:145], v[182:185], v[118:121]
	v_mfma_f32_16x16x32_bf16 v[118:121], v[138:141], v[178:181], v[118:121]
	v_mfma_f32_16x16x32_bf16 v[102:105], v[138:141], v[186:189], v[102:105]
	v_mfma_f32_16x16x32_bf16 v[102:105], v[142:145], v[190:193], v[102:105]
	v_mfma_f32_16x16x32_bf16 v[94:97], v[150:153], v[190:193], v[94:97]
	v_mfma_f32_16x16x32_bf16 v[94:97], v[146:149], v[186:189], v[94:97]
	v_mfma_f32_16x16x32_bf16 v[74:77], v[162:165], v[186:189], v[74:77]
	v_mfma_f32_16x16x32_bf16 v[74:77], v[166:169], v[190:193], v[74:77]
	v_mfma_f32_16x16x32_bf16 v[82:85], v[158:161], v[190:193], v[82:85]
	v_mfma_f32_16x16x32_bf16 v[82:85], v[154:157], v[186:189], v[82:85]
	v_mfma_f32_16x16x32_bf16 v[70:73], v[154:157], v[202:205], v[70:73]
	v_mfma_f32_16x16x32_bf16 v[70:73], v[158:161], v[206:209], v[70:73]
	v_mfma_f32_16x16x32_bf16 v[66:69], v[166:169], v[206:209], v[66:69]
	v_mfma_f32_16x16x32_bf16 v[66:69], v[162:165], v[202:205], v[66:69]
	v_mfma_f32_16x16x32_bf16 v[78:81], v[146:149], v[202:205], v[78:81]
	v_mfma_f32_16x16x32_bf16 v[78:81], v[150:153], v[206:209], v[78:81]
	v_mfma_f32_16x16x32_bf16 v[86:89], v[142:145], v[206:209], v[86:89]
	v_mfma_f32_16x16x32_bf16 v[86:89], v[138:141], v[202:205], v[86:89]
	s_barrier
	s_setprio 0
	s_mov_b32 m0, s70
	v_lshl_add_u64 v[134:135], s[38:39], 0, v[132:133]
	ds_read_b128 v[170:173], v137 offset:16384
	ds_read_b128 v[174:177], v137 offset:17408
	ds_read_b128 v[178:181], v137 offset:18432
	ds_read_b128 v[182:185], v137 offset:19456
	ds_read_b128 v[186:189], v137 offset:20480
	ds_read_b128 v[190:193], v137 offset:21504
	ds_read_b128 v[202:205], v137 offset:22528
	ds_read_b128 v[206:209], v137 offset:23552
	global_load_lds_dwordx4 v[134:135], off
	v_lshl_add_u64 v[210:211], s[38:39], 0, v[130:131]
	s_mov_b32 m0, s67
	v_lshl_add_u64 v[212:213], s[46:47], 0, v[132:133]
	global_load_lds_dwordx4 v[210:211], off
	s_mov_b32 m0, s69
	v_lshl_add_u64 v[214:215], s[36:37], 0, v[130:131]
	global_load_lds_dwordx4 v[212:213], off
	v_lshl_add_u64 v[212:213], s[46:47], 0, v[130:131]
	s_mov_b32 m0, s68
	s_nop 0
	global_load_lds_dwordx4 v[212:213], off
	v_lshl_add_u64 v[212:213], s[36:37], 0, v[132:133]
	s_mov_b32 m0, s53
	s_nop 0
	global_load_lds_dwordx4 v[212:213], off
	s_mov_b32 m0, s56
	s_nop 0
	global_load_lds_dwordx4 v[214:215], off
	s_waitcnt vmcnt(8)
	s_waitcnt lgkmcnt(0)
	s_setprio 1
	s_barrier
	v_mfma_f32_16x16x32_bf16 v[62:65], v[138:141], v[170:173], v[62:65]
	v_mfma_f32_16x16x32_bf16 v[62:65], v[142:145], v[174:177], v[62:65]
	v_mfma_f32_16x16x32_bf16 v[58:61], v[150:153], v[174:177], v[58:61]
	v_mfma_f32_16x16x32_bf16 v[58:61], v[146:149], v[170:173], v[58:61]
	v_mfma_f32_16x16x32_bf16 v[42:45], v[162:165], v[170:173], v[42:45]
	v_mfma_f32_16x16x32_bf16 v[42:45], v[166:169], v[174:177], v[42:45]
	v_mfma_f32_16x16x32_bf16 v[50:53], v[158:161], v[174:177], v[50:53]
	v_mfma_f32_16x16x32_bf16 v[50:53], v[154:157], v[170:173], v[50:53]
	v_mfma_f32_16x16x32_bf16 v[34:37], v[154:157], v[178:181], v[34:37]
	v_mfma_f32_16x16x32_bf16 v[34:37], v[158:161], v[182:185], v[34:37]
	v_mfma_f32_16x16x32_bf16 v[26:29], v[166:169], v[182:185], v[26:29]
	v_mfma_f32_16x16x32_bf16 v[26:29], v[162:165], v[178:181], v[26:29]
	v_mfma_f32_16x16x32_bf16 v[46:49], v[146:149], v[178:181], v[46:49]
	v_mfma_f32_16x16x32_bf16 v[46:49], v[150:153], v[182:185], v[46:49]
	v_mfma_f32_16x16x32_bf16 v[54:57], v[142:145], v[182:185], v[54:57]
	v_mfma_f32_16x16x32_bf16 v[54:57], v[138:141], v[178:181], v[54:57]
	v_mfma_f32_16x16x32_bf16 v[38:41], v[138:141], v[186:189], v[38:41]
	v_mfma_f32_16x16x32_bf16 v[38:41], v[142:145], v[190:193], v[38:41]
	v_mfma_f32_16x16x32_bf16 v[30:33], v[150:153], v[190:193], v[30:33]
	v_mfma_f32_16x16x32_bf16 v[30:33], v[146:149], v[186:189], v[30:33]
	v_mfma_f32_16x16x32_bf16 v[10:13], v[162:165], v[186:189], v[10:13]
	v_mfma_f32_16x16x32_bf16 v[10:13], v[166:169], v[190:193], v[10:13]
	v_mfma_f32_16x16x32_bf16 v[18:21], v[158:161], v[190:193], v[18:21]
	v_mfma_f32_16x16x32_bf16 v[18:21], v[154:157], v[186:189], v[18:21]
	v_mfma_f32_16x16x32_bf16 v[6:9], v[154:157], v[202:205], v[6:9]
	v_mfma_f32_16x16x32_bf16 v[6:9], v[158:161], v[206:209], v[6:9]
	v_mfma_f32_16x16x32_bf16 v[2:5], v[166:169], v[206:209], v[2:5]
	v_mfma_f32_16x16x32_bf16 v[2:5], v[162:165], v[202:205], v[2:5]
	v_mfma_f32_16x16x32_bf16 v[14:17], v[146:149], v[202:205], v[14:17]
	v_mfma_f32_16x16x32_bf16 v[14:17], v[150:153], v[206:209], v[14:17]
	v_mfma_f32_16x16x32_bf16 v[22:25], v[142:145], v[206:209], v[22:25]
	v_mfma_f32_16x16x32_bf16 v[22:25], v[138:141], v[202:205], v[22:25]
	s_barrier
	s_setprio 0
	v_add_u32_e32 v150, s66, v136
	v_add_u32_e32 v166, s65, v136
	ds_read_b128 v[138:141], v150
	ds_read_b128 v[142:145], v150 offset:1024
	ds_read_b128 v[146:149], v150 offset:2048
	ds_read_b128 v[150:153], v150 offset:3072
	ds_read_b128 v[154:157], v166
	ds_read_b128 v[158:161], v166 offset:1024
	ds_read_b128 v[162:165], v166 offset:2048
	ds_read_b128 v[166:169], v166 offset:3072
	s_mov_b32 m0, s57
	v_lshl_add_u64 v[216:217], s[30:31], 0, v[132:133]
	ds_read_b128 v[170:173], v137 offset:32768
	ds_read_b128 v[174:177], v137 offset:33792
	ds_read_b128 v[178:181], v137 offset:34816
	ds_read_b128 v[182:185], v137 offset:35840
	ds_read_b128 v[186:189], v137 offset:36864
	ds_read_b128 v[190:193], v137 offset:37888
	ds_read_b128 v[202:205], v137 offset:38912
	ds_read_b128 v[206:209], v137 offset:39936
	global_load_lds_dwordx4 v[216:217], off
	v_lshl_add_u64 v[216:217], s[30:31], 0, v[130:131]
	s_mov_b32 m0, s58
	s_nop 0
	global_load_lds_dwordx4 v[216:217], off
	s_waitcnt vmcnt(8)
	s_waitcnt lgkmcnt(0)
	s_setprio 1
	s_barrier
	v_mfma_f32_16x16x32_bf16 v[126:129], v[138:141], v[170:173], v[126:129]
	v_mfma_f32_16x16x32_bf16 v[126:129], v[142:145], v[174:177], v[126:129]
	v_mfma_f32_16x16x32_bf16 v[122:125], v[150:153], v[174:177], v[122:125]
	v_mfma_f32_16x16x32_bf16 v[122:125], v[146:149], v[170:173], v[122:125]
	v_mfma_f32_16x16x32_bf16 v[106:109], v[162:165], v[170:173], v[106:109]
	v_mfma_f32_16x16x32_bf16 v[106:109], v[166:169], v[174:177], v[106:109]
	v_mfma_f32_16x16x32_bf16 v[114:117], v[158:161], v[174:177], v[114:117]
	v_mfma_f32_16x16x32_bf16 v[114:117], v[154:157], v[170:173], v[114:117]
	v_mfma_f32_16x16x32_bf16 v[98:101], v[154:157], v[178:181], v[98:101]
	v_mfma_f32_16x16x32_bf16 v[98:101], v[158:161], v[182:185], v[98:101]
	v_mfma_f32_16x16x32_bf16 v[90:93], v[166:169], v[182:185], v[90:93]
	v_mfma_f32_16x16x32_bf16 v[90:93], v[162:165], v[178:181], v[90:93]
	v_mfma_f32_16x16x32_bf16 v[110:113], v[146:149], v[178:181], v[110:113]
	v_mfma_f32_16x16x32_bf16 v[110:113], v[150:153], v[182:185], v[110:113]
	v_mfma_f32_16x16x32_bf16 v[118:121], v[142:145], v[182:185], v[118:121]
	v_mfma_f32_16x16x32_bf16 v[118:121], v[138:141], v[178:181], v[118:121]
	v_mfma_f32_16x16x32_bf16 v[102:105], v[138:141], v[186:189], v[102:105]
	v_mfma_f32_16x16x32_bf16 v[102:105], v[142:145], v[190:193], v[102:105]
	v_mfma_f32_16x16x32_bf16 v[94:97], v[150:153], v[190:193], v[94:97]
	v_mfma_f32_16x16x32_bf16 v[94:97], v[146:149], v[186:189], v[94:97]
	v_mfma_f32_16x16x32_bf16 v[74:77], v[162:165], v[186:189], v[74:77]
	v_mfma_f32_16x16x32_bf16 v[74:77], v[166:169], v[190:193], v[74:77]
	v_mfma_f32_16x16x32_bf16 v[82:85], v[158:161], v[190:193], v[82:85]
	v_mfma_f32_16x16x32_bf16 v[82:85], v[154:157], v[186:189], v[82:85]
	v_mfma_f32_16x16x32_bf16 v[70:73], v[154:157], v[202:205], v[70:73]
	v_mfma_f32_16x16x32_bf16 v[70:73], v[158:161], v[206:209], v[70:73]
	v_mfma_f32_16x16x32_bf16 v[66:69], v[166:169], v[206:209], v[66:69]
	v_mfma_f32_16x16x32_bf16 v[66:69], v[162:165], v[202:205], v[66:69]
	v_mfma_f32_16x16x32_bf16 v[78:81], v[146:149], v[202:205], v[78:81]
	v_mfma_f32_16x16x32_bf16 v[78:81], v[150:153], v[206:209], v[78:81]
	v_mfma_f32_16x16x32_bf16 v[86:89], v[142:145], v[206:209], v[86:89]
	v_mfma_f32_16x16x32_bf16 v[86:89], v[138:141], v[202:205], v[86:89]
	s_barrier
	s_setprio 0
	s_mov_b32 m0, s64
	v_lshl_add_u64 v[134:135], v[134:135], 0, s[10:11]
	ds_read_b128 v[170:173], v137 offset:49152
	ds_read_b128 v[174:177], v137 offset:50176
	ds_read_b128 v[178:181], v137 offset:51200
	ds_read_b128 v[182:185], v137 offset:52224
	ds_read_b128 v[186:189], v137 offset:53248
	ds_read_b128 v[190:193], v137 offset:54272
	ds_read_b128 v[202:205], v137 offset:55296
	ds_read_b128 v[206:209], v137 offset:56320
	global_load_lds_dwordx4 v[134:135], off
	v_lshl_add_u64 v[134:135], v[210:211], 0, s[10:11]
	s_mov_b32 m0, s21
	s_nop 0
	global_load_lds_dwordx4 v[134:135], off
	v_lshl_add_u64 v[134:135], s[28:29], 0, v[132:133]
	s_mov_b32 m0, s72
	s_nop 0
	global_load_lds_dwordx4 v[134:135], off
	v_lshl_add_u64 v[134:135], s[28:29], 0, v[130:131]
	s_mov_b32 m0, s71
	s_nop 0
	global_load_lds_dwordx4 v[134:135], off
	v_lshl_add_u64 v[134:135], v[212:213], 0, s[10:11]
	s_mov_b32 m0, s59
	s_nop 0
	global_load_lds_dwordx4 v[134:135], off
	v_lshl_add_u64 v[134:135], v[214:215], 0, s[10:11]
	s_mov_b32 m0, s60
	s_nop 0
	global_load_lds_dwordx4 v[134:135], off
	s_waitcnt vmcnt(8)
	s_waitcnt lgkmcnt(0)
	s_setprio 1
	s_barrier
	v_mfma_f32_16x16x32_bf16 v[62:65], v[138:141], v[170:173], v[62:65]
	v_mfma_f32_16x16x32_bf16 v[62:65], v[142:145], v[174:177], v[62:65]
	v_mfma_f32_16x16x32_bf16 v[58:61], v[150:153], v[174:177], v[58:61]
	v_mfma_f32_16x16x32_bf16 v[58:61], v[146:149], v[170:173], v[58:61]
	v_mfma_f32_16x16x32_bf16 v[42:45], v[162:165], v[170:173], v[42:45]
	v_mfma_f32_16x16x32_bf16 v[42:45], v[166:169], v[174:177], v[42:45]
	v_mfma_f32_16x16x32_bf16 v[50:53], v[158:161], v[174:177], v[50:53]
	v_mfma_f32_16x16x32_bf16 v[50:53], v[154:157], v[170:173], v[50:53]
	v_mfma_f32_16x16x32_bf16 v[34:37], v[154:157], v[178:181], v[34:37]
	v_mfma_f32_16x16x32_bf16 v[34:37], v[158:161], v[182:185], v[34:37]
	v_mfma_f32_16x16x32_bf16 v[26:29], v[166:169], v[182:185], v[26:29]
	v_mfma_f32_16x16x32_bf16 v[26:29], v[162:165], v[178:181], v[26:29]
	v_mfma_f32_16x16x32_bf16 v[46:49], v[146:149], v[178:181], v[46:49]
	v_mfma_f32_16x16x32_bf16 v[46:49], v[150:153], v[182:185], v[46:49]
	v_mfma_f32_16x16x32_bf16 v[54:57], v[142:145], v[182:185], v[54:57]
	v_mfma_f32_16x16x32_bf16 v[54:57], v[138:141], v[178:181], v[54:57]
	v_mfma_f32_16x16x32_bf16 v[38:41], v[138:141], v[186:189], v[38:41]
	v_mfma_f32_16x16x32_bf16 v[38:41], v[142:145], v[190:193], v[38:41]
	v_mfma_f32_16x16x32_bf16 v[30:33], v[150:153], v[190:193], v[30:33]
	v_mfma_f32_16x16x32_bf16 v[30:33], v[146:149], v[186:189], v[30:33]
	v_mfma_f32_16x16x32_bf16 v[10:13], v[162:165], v[186:189], v[10:13]
	v_mfma_f32_16x16x32_bf16 v[10:13], v[166:169], v[190:193], v[10:13]
	v_mfma_f32_16x16x32_bf16 v[18:21], v[158:161], v[190:193], v[18:21]
	v_mfma_f32_16x16x32_bf16 v[18:21], v[154:157], v[186:189], v[18:21]
	v_mfma_f32_16x16x32_bf16 v[6:9], v[154:157], v[202:205], v[6:9]
	v_mfma_f32_16x16x32_bf16 v[6:9], v[158:161], v[206:209], v[6:9]
	v_mfma_f32_16x16x32_bf16 v[2:5], v[166:169], v[206:209], v[2:5]
	v_mfma_f32_16x16x32_bf16 v[2:5], v[162:165], v[202:205], v[2:5]
	v_mfma_f32_16x16x32_bf16 v[14:17], v[146:149], v[202:205], v[14:17]
	v_mfma_f32_16x16x32_bf16 v[14:17], v[150:153], v[206:209], v[14:17]
	v_mfma_f32_16x16x32_bf16 v[22:25], v[142:145], v[206:209], v[22:25]
	v_mfma_f32_16x16x32_bf16 v[22:25], v[138:141], v[202:205], v[22:25]
	s_barrier
	s_setprio 0
	s_andn2_b64 vcc, exec, s[26:27]
	s_mov_b64 s[28:29], -1
	s_mov_b64 s[26:27], 0
	s_movk_i32 s21, 0x100
	s_cbranch_vccz .LBB0_1002
	s_and_b64 vcc, exec, s[16:17]
	s_cbranch_vccz .LBB0_1005
	s_barrier

.LBB0_1087:
	s_add_u32 s30, s28, 0xfff80080
	s_addc_u32 s31, s29, -1
	s_cmp_eq_u32 s83, 28
	s_cselect_b32 s43, s23, s31
	s_cselect_b32 s42, s44, s30
	s_cselect_b32 s31, s21, s82
	s_cselect_b32 s30, s45, s81
	s_add_i32 s84, 0, 0x10000
	s_add_i32 s86, 0, 0x14000
	v_add_u32_e32 v62, s84, v229
	v_add_u32_e32 v158, s86, v229
	ds_read_b128 v[42:45], v62
	ds_read_b128 v[46:49], v62 offset:1024
	ds_read_b128 v[58:61], v62 offset:2048
	ds_read_b128 v[62:65], v62 offset:3072
	ds_read_b128 v[146:149], v158
	ds_read_b128 v[150:153], v158 offset:1024
	ds_read_b128 v[154:157], v158 offset:2048
	ds_read_b128 v[158:161], v158 offset:3072
	v_lshl_add_u64 v[208:209], s[28:29], 0, v[204:205]
	s_add_i32 m0, s71, 0xc000
	ds_read_b128 v[162:165], v230
	ds_read_b128 v[166:169], v230 offset:1024
	ds_read_b128 v[170:173], v230 offset:2048
	ds_read_b128 v[174:177], v230 offset:3072
	ds_read_b128 v[178:181], v230 offset:4096
	ds_read_b128 v[182:185], v230 offset:5120
	ds_read_b128 v[186:189], v230 offset:6144
	ds_read_b128 v[190:193], v230 offset:7168
	global_load_lds_dwordx4 v[208:209], off
	v_lshl_add_u64 v[208:209], s[28:29], 0, v[206:207]
	s_add_i32 m0, s71, 0xe000
	s_nop 0
	global_load_lds_dwordx4 v[208:209], off
	s_waitcnt vmcnt(8)
	s_waitcnt lgkmcnt(0)
	s_setprio 1
	s_barrier
	v_mfma_f32_16x16x32_bf16 v[142:145], v[42:45], v[162:165], v[142:145]
	v_mfma_f32_16x16x32_bf16 v[142:145], v[46:49], v[166:169], v[142:145]
	v_mfma_f32_16x16x32_bf16 v[138:141], v[62:65], v[166:169], v[138:141]
	v_mfma_f32_16x16x32_bf16 v[138:141], v[58:61], v[162:165], v[138:141]
	v_mfma_f32_16x16x32_bf16 v[130:133], v[154:157], v[162:165], v[130:133]
	v_mfma_f32_16x16x32_bf16 v[130:133], v[158:161], v[166:169], v[130:133]
	v_mfma_f32_16x16x32_bf16 v[134:137], v[150:153], v[166:169], v[134:137]
	v_mfma_f32_16x16x32_bf16 v[134:137], v[146:149], v[162:165], v[134:137]
	v_mfma_f32_16x16x32_bf16 v[118:121], v[146:149], v[170:173], v[118:121]
	v_mfma_f32_16x16x32_bf16 v[118:121], v[150:153], v[174:177], v[118:121]
	v_mfma_f32_16x16x32_bf16 v[114:117], v[158:161], v[174:177], v[114:117]
	v_mfma_f32_16x16x32_bf16 v[114:117], v[154:157], v[170:173], v[114:117]
	v_mfma_f32_16x16x32_bf16 v[122:125], v[58:61], v[170:173], v[122:125]
	v_mfma_f32_16x16x32_bf16 v[122:125], v[62:65], v[174:177], v[122:125]
	v_mfma_f32_16x16x32_bf16 v[126:129], v[46:49], v[174:177], v[126:129]
	v_mfma_f32_16x16x32_bf16 v[126:129], v[42:45], v[170:173], v[126:129]
	v_mfma_f32_16x16x32_bf16 v[110:113], v[42:45], v[178:181], v[110:113]
	v_mfma_f32_16x16x32_bf16 v[110:113], v[46:49], v[182:185], v[110:113]
	v_mfma_f32_16x16x32_bf16 v[106:109], v[62:65], v[182:185], v[106:109]
	v_mfma_f32_16x16x32_bf16 v[106:109], v[58:61], v[178:181], v[106:109]
	v_mfma_f32_16x16x32_bf16 v[98:101], v[154:157], v[178:181], v[98:101]
	v_mfma_f32_16x16x32_bf16 v[98:101], v[158:161], v[182:185], v[98:101]
	v_mfma_f32_16x16x32_bf16 v[102:105], v[150:153], v[182:185], v[102:105]
	v_mfma_f32_16x16x32_bf16 v[102:105], v[146:149], v[178:181], v[102:105]
	v_mfma_f32_16x16x32_bf16 v[86:89], v[146:149], v[186:189], v[86:89]
	v_mfma_f32_16x16x32_bf16 v[86:89], v[150:153], v[190:193], v[86:89]
	v_mfma_f32_16x16x32_bf16 v[82:85], v[158:161], v[190:193], v[82:85]
	v_mfma_f32_16x16x32_bf16 v[82:85], v[154:157], v[186:189], v[82:85]
	v_mfma_f32_16x16x32_bf16 v[90:93], v[58:61], v[186:189], v[90:93]
	v_mfma_f32_16x16x32_bf16 v[90:93], v[62:65], v[190:193], v[90:93]
	v_mfma_f32_16x16x32_bf16 v[94:97], v[46:49], v[190:193], v[94:97]
	v_mfma_f32_16x16x32_bf16 v[94:97], v[42:45], v[186:189], v[94:97]
	s_barrier
	s_setprio 0
	s_add_i32 s84, s84, s70
	v_lshl_add_u64 v[208:209], s[30:31], 0, v[194:195]
	s_mov_b32 m0, s84
	ds_read_b128 v[162:165], v230 offset:16384
	ds_read_b128 v[166:169], v230 offset:17408
	ds_read_b128 v[170:173], v230 offset:18432
	ds_read_b128 v[174:177], v230 offset:19456
	ds_read_b128 v[178:181], v230 offset:20480
	ds_read_b128 v[182:185], v230 offset:21504
	ds_read_b128 v[186:189], v230 offset:22528
	ds_read_b128 v[190:193], v230 offset:23552
	global_load_lds_dwordx4 v[208:209], off
	s_add_i32 m0, s84, 0x2000
	s_add_u32 s84, s30, 0x80000
	v_lshl_add_u64 v[210:211], s[30:31], 0, v[202:203]
	s_addc_u32 s85, s31, 0
	s_add_i32 s86, s86, s70
	global_load_lds_dwordx4 v[210:211], off
	v_lshl_add_u64 v[212:213], s[84:85], 0, v[194:195]
	s_mov_b32 m0, s86
	v_lshl_add_u64 v[214:215], s[42:43], 0, v[202:203]
	global_load_lds_dwordx4 v[212:213], off
	v_lshl_add_u64 v[212:213], s[84:85], 0, v[202:203]
	s_add_i32 m0, s86, 0x2000
	s_nop 0
	global_load_lds_dwordx4 v[212:213], off
	v_lshl_add_u64 v[212:213], s[42:43], 0, v[194:195]
	s_mov_b32 m0, s71
	s_nop 0
	global_load_lds_dwordx4 v[212:213], off
	s_mov_b32 m0, s72
	s_nop 0
	global_load_lds_dwordx4 v[214:215], off
	s_waitcnt vmcnt(8)
	s_waitcnt lgkmcnt(0)
	s_setprio 1
	s_barrier
	v_mfma_f32_16x16x32_bf16 v[78:81], v[42:45], v[162:165], v[78:81]
	v_mfma_f32_16x16x32_bf16 v[78:81], v[46:49], v[166:169], v[78:81]
	v_mfma_f32_16x16x32_bf16 v[74:77], v[62:65], v[166:169], v[74:77]
	v_mfma_f32_16x16x32_bf16 v[74:77], v[58:61], v[162:165], v[74:77]
	v_mfma_f32_16x16x32_bf16 v[50:53], v[58:61], v[170:173], v[50:53]
	v_mfma_f32_16x16x32_bf16 v[50:53], v[62:65], v[174:177], v[50:53]
	v_mfma_f32_16x16x32_bf16 v[54:57], v[46:49], v[174:177], v[54:57]
	v_mfma_f32_16x16x32_bf16 v[54:57], v[42:45], v[170:173], v[54:57]
	v_mfma_f32_16x16x32_bf16 v[30:33], v[42:45], v[178:181], v[30:33]
	v_mfma_f32_16x16x32_bf16 v[30:33], v[46:49], v[182:185], v[30:33]
	v_mfma_f32_16x16x32_bf16 v[26:29], v[62:65], v[182:185], v[26:29]
	v_mfma_f32_16x16x32_bf16 v[26:29], v[58:61], v[178:181], v[26:29]
	v_mfma_f32_16x16x32_bf16 v[10:13], v[58:61], v[186:189], v[10:13]
	v_mfma_f32_16x16x32_bf16 v[10:13], v[62:65], v[190:193], v[10:13]
	v_mfma_f32_16x16x32_bf16 v[14:17], v[46:49], v[190:193], v[14:17]
	v_mfma_f32_16x16x32_bf16 v[14:17], v[42:45], v[186:189], v[14:17]
	v_mfma_f32_16x16x32_bf16 v[38:41], v[146:149], v[170:173], v[38:41]
	v_mfma_f32_16x16x32_bf16 v[34:37], v[154:157], v[170:173], v[34:37]
	v_mfma_f32_16x16x32_bf16 v[22:25], v[146:149], v[178:181], v[22:25]
	v_mfma_f32_16x16x32_bf16 v[18:21], v[154:157], v[178:181], v[18:21]
	v_mfma_f32_16x16x32_bf16 v[6:9], v[146:149], v[186:189], v[6:9]
	v_mfma_f32_16x16x32_bf16 v[2:5], v[154:157], v[186:189], v[2:5]
	v_mfma_f32_16x16x32_bf16 v[42:45], v[146:149], v[162:165], v[70:73]
	v_mfma_f32_16x16x32_bf16 v[46:49], v[154:157], v[162:165], v[66:69]
	v_mfma_f32_16x16x32_bf16 v[38:41], v[150:153], v[174:177], v[38:41]
	v_mfma_f32_16x16x32_bf16 v[34:37], v[158:161], v[174:177], v[34:37]
	v_mfma_f32_16x16x32_bf16 v[22:25], v[150:153], v[182:185], v[22:25]
	v_mfma_f32_16x16x32_bf16 v[18:21], v[158:161], v[182:185], v[18:21]
	v_mfma_f32_16x16x32_bf16 v[6:9], v[150:153], v[190:193], v[6:9]
	v_mfma_f32_16x16x32_bf16 v[2:5], v[158:161], v[190:193], v[2:5]
	v_mfma_f32_16x16x32_bf16 v[42:45], v[150:153], v[166:169], v[42:45]
	v_mfma_f32_16x16x32_bf16 v[46:49], v[158:161], v[166:169], v[46:49]
	s_barrier
	s_setprio 0
	s_add_i32 s84, 0, 0x18000
	s_add_i32 s85, 0, 0x1c000
	v_add_u32_e32 v70, s84, v229
	v_add_u32_e32 v158, s85, v229
	ds_read_b128 v[58:61], v70
	ds_read_b128 v[62:65], v70 offset:1024
	ds_read_b128 v[66:69], v70 offset:2048
	ds_read_b128 v[70:73], v70 offset:3072
	ds_read_b128 v[146:149], v158
	ds_read_b128 v[150:153], v158 offset:1024
	ds_read_b128 v[154:157], v158 offset:2048
	ds_read_b128 v[158:161], v158 offset:3072
	s_add_u32 s42, s42, 0x80000
	s_addc_u32 s43, s43, 0
	s_mov_b32 m0, s73
	v_lshl_add_u64 v[216:217], s[42:43], 0, v[194:195]
	ds_read_b128 v[162:165], v230 offset:32768
	ds_read_b128 v[166:169], v230 offset:33792
	ds_read_b128 v[170:173], v230 offset:34816
	ds_read_b128 v[174:177], v230 offset:35840
	ds_read_b128 v[178:181], v230 offset:36864
	ds_read_b128 v[182:185], v230 offset:37888
	ds_read_b128 v[186:189], v230 offset:38912
	ds_read_b128 v[190:193], v230 offset:39936
	global_load_lds_dwordx4 v[216:217], off
	v_lshl_add_u64 v[216:217], s[42:43], 0, v[202:203]
	s_mov_b32 m0, s74
	s_nop 0
	global_load_lds_dwordx4 v[216:217], off
	s_waitcnt vmcnt(8)
	s_waitcnt lgkmcnt(0)
	s_setprio 1
	s_barrier
	v_mfma_f32_16x16x32_bf16 v[142:145], v[58:61], v[162:165], v[142:145]
	v_mfma_f32_16x16x32_bf16 v[142:145], v[62:65], v[166:169], v[142:145]
	v_mfma_f32_16x16x32_bf16 v[138:141], v[70:73], v[166:169], v[138:141]
	v_mfma_f32_16x16x32_bf16 v[138:141], v[66:69], v[162:165], v[138:141]
	v_mfma_f32_16x16x32_bf16 v[130:133], v[154:157], v[162:165], v[130:133]
	v_mfma_f32_16x16x32_bf16 v[130:133], v[158:161], v[166:169], v[130:133]
	v_mfma_f32_16x16x32_bf16 v[134:137], v[150:153], v[166:169], v[134:137]
	v_mfma_f32_16x16x32_bf16 v[134:137], v[146:149], v[162:165], v[134:137]
	v_mfma_f32_16x16x32_bf16 v[118:121], v[146:149], v[170:173], v[118:121]
	v_mfma_f32_16x16x32_bf16 v[118:121], v[150:153], v[174:177], v[118:121]
	v_mfma_f32_16x16x32_bf16 v[114:117], v[158:161], v[174:177], v[114:117]
	v_mfma_f32_16x16x32_bf16 v[114:117], v[154:157], v[170:173], v[114:117]
	v_mfma_f32_16x16x32_bf16 v[122:125], v[66:69], v[170:173], v[122:125]
	v_mfma_f32_16x16x32_bf16 v[122:125], v[70:73], v[174:177], v[122:125]
	v_mfma_f32_16x16x32_bf16 v[126:129], v[62:65], v[174:177], v[126:129]
	v_mfma_f32_16x16x32_bf16 v[126:129], v[58:61], v[170:173], v[126:129]
	v_mfma_f32_16x16x32_bf16 v[110:113], v[58:61], v[178:181], v[110:113]
	v_mfma_f32_16x16x32_bf16 v[110:113], v[62:65], v[182:185], v[110:113]
	v_mfma_f32_16x16x32_bf16 v[106:109], v[70:73], v[182:185], v[106:109]
	v_mfma_f32_16x16x32_bf16 v[106:109], v[66:69], v[178:181], v[106:109]
	v_mfma_f32_16x16x32_bf16 v[98:101], v[154:157], v[178:181], v[98:101]
	v_mfma_f32_16x16x32_bf16 v[98:101], v[158:161], v[182:185], v[98:101]
	v_mfma_f32_16x16x32_bf16 v[102:105], v[150:153], v[182:185], v[102:105]
	v_mfma_f32_16x16x32_bf16 v[102:105], v[146:149], v[178:181], v[102:105]
	v_mfma_f32_16x16x32_bf16 v[86:89], v[146:149], v[186:189], v[86:89]
	v_mfma_f32_16x16x32_bf16 v[86:89], v[150:153], v[190:193], v[86:89]
	v_mfma_f32_16x16x32_bf16 v[82:85], v[158:161], v[190:193], v[82:85]
	v_mfma_f32_16x16x32_bf16 v[82:85], v[154:157], v[186:189], v[82:85]
	v_mfma_f32_16x16x32_bf16 v[90:93], v[66:69], v[186:189], v[90:93]
	v_mfma_f32_16x16x32_bf16 v[90:93], v[70:73], v[190:193], v[90:93]
	v_mfma_f32_16x16x32_bf16 v[94:97], v[62:65], v[190:193], v[94:97]
	v_mfma_f32_16x16x32_bf16 v[94:97], v[58:61], v[186:189], v[94:97]
	s_barrier
	s_setprio 0
	s_add_i32 s42, s84, s70
	v_lshl_add_u64 v[208:209], v[208:209], 0, s[10:11]
	s_mov_b32 m0, s42
	ds_read_b128 v[162:165], v230 offset:49152
	ds_read_b128 v[166:169], v230 offset:50176
	ds_read_b128 v[170:173], v230 offset:51200
	ds_read_b128 v[174:177], v230 offset:52224
	ds_read_b128 v[178:181], v230 offset:53248
	ds_read_b128 v[182:185], v230 offset:54272
	ds_read_b128 v[186:189], v230 offset:55296
	ds_read_b128 v[190:193], v230 offset:56320
	global_load_lds_dwordx4 v[208:209], off
	s_add_i32 m0, s42, 0x2000
	s_add_u32 s30, s30, 0x80080
	v_lshl_add_u64 v[208:209], v[210:211], 0, s[10:11]
	s_addc_u32 s31, s31, 0
	s_add_i32 s42, s85, s70
	global_load_lds_dwordx4 v[208:209], off
	v_lshl_add_u64 v[208:209], s[30:31], 0, v[194:195]
	s_mov_b32 m0, s42
	s_nop 0
	global_load_lds_dwordx4 v[208:209], off
	v_lshl_add_u64 v[208:209], s[30:31], 0, v[202:203]
	s_add_i32 m0, s42, 0x2000
	s_nop 0
	global_load_lds_dwordx4 v[208:209], off
	v_lshl_add_u64 v[208:209], v[212:213], 0, s[10:11]
	s_mov_b32 m0, s79
	s_nop 0
	global_load_lds_dwordx4 v[208:209], off
	v_lshl_add_u64 v[208:209], v[214:215], 0, s[10:11]
	s_mov_b32 m0, s80
	s_nop 0
	global_load_lds_dwordx4 v[208:209], off
	s_waitcnt vmcnt(8)
	s_waitcnt lgkmcnt(0)
	s_setprio 1
	s_barrier
	v_mfma_f32_16x16x32_bf16 v[78:81], v[58:61], v[162:165], v[78:81]
	v_mfma_f32_16x16x32_bf16 v[78:81], v[62:65], v[166:169], v[78:81]
	v_mfma_f32_16x16x32_bf16 v[74:77], v[70:73], v[166:169], v[74:77]
	v_mfma_f32_16x16x32_bf16 v[74:77], v[66:69], v[162:165], v[74:77]
	v_mfma_f32_16x16x32_bf16 v[50:53], v[66:69], v[170:173], v[50:53]
	v_mfma_f32_16x16x32_bf16 v[50:53], v[70:73], v[174:177], v[50:53]
	v_mfma_f32_16x16x32_bf16 v[54:57], v[62:65], v[174:177], v[54:57]
	v_mfma_f32_16x16x32_bf16 v[54:57], v[58:61], v[170:173], v[54:57]
	v_mfma_f32_16x16x32_bf16 v[30:33], v[58:61], v[178:181], v[30:33]
	v_mfma_f32_16x16x32_bf16 v[30:33], v[62:65], v[182:185], v[30:33]
	v_mfma_f32_16x16x32_bf16 v[26:29], v[70:73], v[182:185], v[26:29]
	v_mfma_f32_16x16x32_bf16 v[26:29], v[66:69], v[178:181], v[26:29]
	v_mfma_f32_16x16x32_bf16 v[10:13], v[66:69], v[186:189], v[10:13]
	v_mfma_f32_16x16x32_bf16 v[10:13], v[70:73], v[190:193], v[10:13]
	v_mfma_f32_16x16x32_bf16 v[14:17], v[62:65], v[190:193], v[14:17]
	v_mfma_f32_16x16x32_bf16 v[14:17], v[58:61], v[186:189], v[14:17]
	v_mfma_f32_16x16x32_bf16 v[42:45], v[146:149], v[162:165], v[42:45]
	v_mfma_f32_16x16x32_bf16 v[70:73], v[150:153], v[166:169], v[42:45]
	v_mfma_f32_16x16x32_bf16 v[42:45], v[154:157], v[162:165], v[46:49]
	v_mfma_f32_16x16x32_bf16 v[38:41], v[146:149], v[170:173], v[38:41]
	v_mfma_f32_16x16x32_bf16 v[34:37], v[154:157], v[170:173], v[34:37]
	v_mfma_f32_16x16x32_bf16 v[22:25], v[146:149], v[178:181], v[22:25]
	v_mfma_f32_16x16x32_bf16 v[18:21], v[154:157], v[178:181], v[18:21]
	v_mfma_f32_16x16x32_bf16 v[6:9], v[146:149], v[186:189], v[6:9]
	v_mfma_f32_16x16x32_bf16 v[2:5], v[154:157], v[186:189], v[2:5]
	v_mfma_f32_16x16x32_bf16 v[66:69], v[158:161], v[166:169], v[42:45]
	v_mfma_f32_16x16x32_bf16 v[38:41], v[150:153], v[174:177], v[38:41]
	v_mfma_f32_16x16x32_bf16 v[34:37], v[158:161], v[174:177], v[34:37]
	v_mfma_f32_16x16x32_bf16 v[22:25], v[150:153], v[182:185], v[22:25]
	v_mfma_f32_16x16x32_bf16 v[18:21], v[158:161], v[182:185], v[18:21]
	v_mfma_f32_16x16x32_bf16 v[6:9], v[150:153], v[190:193], v[6:9]
	v_mfma_f32_16x16x32_bf16 v[2:5], v[158:161], v[190:193], v[2:5]
	s_barrier
	s_setprio 0
	s_add_i32 s83, s83, 2
	s_add_u32 s28, s28, 0x100
	s_addc_u32 s29, s29, 0
	s_add_u32 s81, s81, 0x100
	s_addc_u32 s82, s82, 0
	s_cmp_gt_u32 s83, 29
	s_cbranch_scc0 .LBB0_1087
	s_and_b64 vcc, exec, s[16:17]
	s_cbranch_vccz .LBB0_1090
	s_barrier

.LBB0_1272:
	s_add_u32 s30, s28, 0xfff80080
	s_addc_u32 s31, s29, -1
	s_add_i32 s66, 0, 0x10000
	s_cmp_eq_u32 s65, 28
	s_cselect_b32 s37, s60, s31
	s_cselect_b32 s36, s61, s30
	s_cselect_b32 s31, s21, s64
	s_cselect_b32 s30, s62, s63
	s_add_i32 s68, 0, 0x14000
	v_add_u32_e32 v126, s66, v156
	v_add_u32_e32 v154, s68, v156
	ds_read_b128 v[114:117], v126
	ds_read_b128 v[118:121], v126 offset:1024
	ds_read_b128 v[122:125], v126 offset:2048
	ds_read_b128 v[126:129], v126 offset:3072
	ds_read_b128 v[158:161], v154
	ds_read_b128 v[162:165], v154 offset:1024
	ds_read_b128 v[166:169], v154 offset:2048
	ds_read_b128 v[170:173], v154 offset:3072
	v_lshl_add_u64 v[154:155], s[28:29], 0, v[150:151]
	s_add_i32 m0, s49, 0xc000
	ds_read_b128 v[174:177], v157
	ds_read_b128 v[178:181], v157 offset:1024
	ds_read_b128 v[182:185], v157 offset:2048
	ds_read_b128 v[186:189], v157 offset:3072
	ds_read_b128 v[190:193], v157 offset:4096
	ds_read_b128 v[202:205], v157 offset:5120
	ds_read_b128 v[206:209], v157 offset:6144
	ds_read_b128 v[210:213], v157 offset:7168
	global_load_lds_dwordx4 v[154:155], off
	v_lshl_add_u64 v[154:155], s[28:29], 0, v[152:153]
	s_add_i32 m0, s49, 0xe000
	s_nop 0
	global_load_lds_dwordx4 v[154:155], off
	s_waitcnt vmcnt(8)
	s_waitcnt lgkmcnt(0)
	s_setprio 1
	s_barrier
	v_mfma_f32_16x16x32_bf16 v[142:145], v[114:117], v[174:177], v[142:145]
	v_mfma_f32_16x16x32_bf16 v[142:145], v[118:121], v[178:181], v[142:145]
	v_mfma_f32_16x16x32_bf16 v[138:141], v[126:129], v[178:181], v[138:141]
	v_mfma_f32_16x16x32_bf16 v[138:141], v[122:125], v[174:177], v[138:141]
	v_mfma_f32_16x16x32_bf16 v[130:133], v[166:169], v[174:177], v[130:133]
	v_mfma_f32_16x16x32_bf16 v[130:133], v[170:173], v[178:181], v[130:133]
	v_mfma_f32_16x16x32_bf16 v[134:137], v[162:165], v[178:181], v[134:137]
	v_mfma_f32_16x16x32_bf16 v[134:137], v[158:161], v[174:177], v[134:137]
	v_mfma_f32_16x16x32_bf16 v[102:105], v[158:161], v[182:185], v[102:105]
	v_mfma_f32_16x16x32_bf16 v[102:105], v[162:165], v[186:189], v[102:105]
	v_mfma_f32_16x16x32_bf16 v[98:101], v[170:173], v[186:189], v[98:101]
	v_mfma_f32_16x16x32_bf16 v[98:101], v[166:169], v[182:185], v[98:101]
	v_mfma_f32_16x16x32_bf16 v[106:109], v[122:125], v[182:185], v[106:109]
	v_mfma_f32_16x16x32_bf16 v[106:109], v[126:129], v[186:189], v[106:109]
	v_mfma_f32_16x16x32_bf16 v[110:113], v[118:121], v[186:189], v[110:113]
	v_mfma_f32_16x16x32_bf16 v[110:113], v[114:117], v[182:185], v[110:113]
	v_mfma_f32_16x16x32_bf16 v[94:97], v[114:117], v[190:193], v[94:97]
	v_mfma_f32_16x16x32_bf16 v[94:97], v[118:121], v[202:205], v[94:97]
	v_mfma_f32_16x16x32_bf16 v[90:93], v[126:129], v[202:205], v[90:93]
	v_mfma_f32_16x16x32_bf16 v[90:93], v[122:125], v[190:193], v[90:93]
	v_mfma_f32_16x16x32_bf16 v[82:85], v[166:169], v[190:193], v[82:85]
	v_mfma_f32_16x16x32_bf16 v[82:85], v[170:173], v[202:205], v[82:85]
	v_mfma_f32_16x16x32_bf16 v[86:89], v[162:165], v[202:205], v[86:89]
	v_mfma_f32_16x16x32_bf16 v[86:89], v[158:161], v[190:193], v[86:89]
	v_mfma_f32_16x16x32_bf16 v[70:73], v[158:161], v[206:209], v[70:73]
	v_mfma_f32_16x16x32_bf16 v[70:73], v[162:165], v[210:213], v[70:73]
	v_mfma_f32_16x16x32_bf16 v[66:69], v[170:173], v[210:213], v[66:69]
	v_mfma_f32_16x16x32_bf16 v[66:69], v[166:169], v[206:209], v[66:69]
	v_mfma_f32_16x16x32_bf16 v[74:77], v[122:125], v[206:209], v[74:77]
	v_mfma_f32_16x16x32_bf16 v[74:77], v[126:129], v[210:213], v[74:77]
	v_mfma_f32_16x16x32_bf16 v[78:81], v[118:121], v[210:213], v[78:81]
	v_mfma_f32_16x16x32_bf16 v[78:81], v[114:117], v[206:209], v[78:81]
	s_barrier
	s_setprio 0
	s_add_i32 s66, s66, s48
	v_lshl_add_u64 v[154:155], s[30:31], 0, v[146:147]
	s_mov_b32 m0, s66
	ds_read_b128 v[174:177], v157 offset:16384
	ds_read_b128 v[178:181], v157 offset:17408
	ds_read_b128 v[182:185], v157 offset:18432
	ds_read_b128 v[186:189], v157 offset:19456
	ds_read_b128 v[190:193], v157 offset:20480
	ds_read_b128 v[202:205], v157 offset:21504
	ds_read_b128 v[206:209], v157 offset:22528
	ds_read_b128 v[210:213], v157 offset:23552
	global_load_lds_dwordx4 v[154:155], off
	s_add_i32 m0, s66, 0x2000
	s_add_u32 s66, s30, 0x80000
	v_lshl_add_u64 v[214:215], s[30:31], 0, v[148:149]
	s_addc_u32 s67, s31, 0
	s_add_i32 s68, s68, s48
	global_load_lds_dwordx4 v[214:215], off
	v_lshl_add_u64 v[216:217], s[66:67], 0, v[146:147]
	s_mov_b32 m0, s68
	v_lshl_add_u64 v[228:229], s[36:37], 0, v[148:149]
	global_load_lds_dwordx4 v[216:217], off
	v_lshl_add_u64 v[216:217], s[66:67], 0, v[148:149]
	s_add_i32 m0, s68, 0x2000
	s_nop 0
	global_load_lds_dwordx4 v[216:217], off
	v_lshl_add_u64 v[216:217], s[36:37], 0, v[146:147]
	s_mov_b32 m0, s49
	s_nop 0
	global_load_lds_dwordx4 v[216:217], off
	s_mov_b32 m0, s50
	s_nop 0
	global_load_lds_dwordx4 v[228:229], off
	s_waitcnt vmcnt(8)
	s_waitcnt lgkmcnt(0)
	s_setprio 1
	s_barrier
	v_mfma_f32_16x16x32_bf16 v[62:65], v[114:117], v[174:177], v[62:65]
	v_mfma_f32_16x16x32_bf16 v[62:65], v[118:121], v[178:181], v[62:65]
	v_mfma_f32_16x16x32_bf16 v[58:61], v[126:129], v[178:181], v[58:61]
	v_mfma_f32_16x16x32_bf16 v[58:61], v[122:125], v[174:177], v[58:61]
	v_mfma_f32_16x16x32_bf16 v[50:53], v[166:169], v[174:177], v[50:53]
	v_mfma_f32_16x16x32_bf16 v[50:53], v[170:173], v[178:181], v[50:53]
	v_mfma_f32_16x16x32_bf16 v[54:57], v[162:165], v[178:181], v[54:57]
	v_mfma_f32_16x16x32_bf16 v[54:57], v[158:161], v[174:177], v[54:57]
	v_mfma_f32_16x16x32_bf16 v[38:41], v[158:161], v[182:185], v[38:41]
	v_mfma_f32_16x16x32_bf16 v[38:41], v[162:165], v[186:189], v[38:41]
	v_mfma_f32_16x16x32_bf16 v[34:37], v[170:173], v[186:189], v[34:37]
	v_mfma_f32_16x16x32_bf16 v[34:37], v[166:169], v[182:185], v[34:37]
	v_mfma_f32_16x16x32_bf16 v[42:45], v[122:125], v[182:185], v[42:45]
	v_mfma_f32_16x16x32_bf16 v[42:45], v[126:129], v[186:189], v[42:45]
	v_mfma_f32_16x16x32_bf16 v[46:49], v[118:121], v[186:189], v[46:49]
	v_mfma_f32_16x16x32_bf16 v[46:49], v[114:117], v[182:185], v[46:49]
	v_mfma_f32_16x16x32_bf16 v[30:33], v[114:117], v[190:193], v[30:33]
	v_mfma_f32_16x16x32_bf16 v[30:33], v[118:121], v[202:205], v[30:33]
	v_mfma_f32_16x16x32_bf16 v[26:29], v[126:129], v[202:205], v[26:29]
	v_mfma_f32_16x16x32_bf16 v[26:29], v[122:125], v[190:193], v[26:29]
	v_mfma_f32_16x16x32_bf16 v[18:21], v[166:169], v[190:193], v[18:21]
	v_mfma_f32_16x16x32_bf16 v[18:21], v[170:173], v[202:205], v[18:21]
	v_mfma_f32_16x16x32_bf16 v[22:25], v[162:165], v[202:205], v[22:25]
	v_mfma_f32_16x16x32_bf16 v[22:25], v[158:161], v[190:193], v[22:25]
	v_mfma_f32_16x16x32_bf16 v[6:9], v[158:161], v[206:209], v[6:9]
	v_mfma_f32_16x16x32_bf16 v[6:9], v[162:165], v[210:213], v[6:9]
	v_mfma_f32_16x16x32_bf16 v[2:5], v[170:173], v[210:213], v[2:5]
	v_mfma_f32_16x16x32_bf16 v[2:5], v[166:169], v[206:209], v[2:5]
	v_mfma_f32_16x16x32_bf16 v[10:13], v[122:125], v[206:209], v[10:13]
	v_mfma_f32_16x16x32_bf16 v[10:13], v[126:129], v[210:213], v[10:13]
	v_mfma_f32_16x16x32_bf16 v[14:17], v[118:121], v[210:213], v[14:17]
	v_mfma_f32_16x16x32_bf16 v[14:17], v[114:117], v[206:209], v[14:17]
	s_barrier
	s_setprio 0
	s_add_i32 s66, 0, 0x18000
	s_add_i32 s67, 0, 0x1c000
	v_add_u32_e32 v126, s66, v156
	v_add_u32_e32 v170, s67, v156
	ds_read_b128 v[114:117], v126
	ds_read_b128 v[118:121], v126 offset:1024
	ds_read_b128 v[122:125], v126 offset:2048
	ds_read_b128 v[126:129], v126 offset:3072
	ds_read_b128 v[158:161], v170
	ds_read_b128 v[162:165], v170 offset:1024
	ds_read_b128 v[166:169], v170 offset:2048
	ds_read_b128 v[170:173], v170 offset:3072
	s_add_u32 s36, s36, 0x80000
	s_addc_u32 s37, s37, 0
	s_mov_b32 m0, s51
	v_lshl_add_u64 v[230:231], s[36:37], 0, v[146:147]
	ds_read_b128 v[174:177], v157 offset:32768
	ds_read_b128 v[178:181], v157 offset:33792
	ds_read_b128 v[182:185], v157 offset:34816
	ds_read_b128 v[186:189], v157 offset:35840
	ds_read_b128 v[190:193], v157 offset:36864
	ds_read_b128 v[202:205], v157 offset:37888
	ds_read_b128 v[206:209], v157 offset:38912
	ds_read_b128 v[210:213], v157 offset:39936
	global_load_lds_dwordx4 v[230:231], off
	v_lshl_add_u64 v[230:231], s[36:37], 0, v[148:149]
	s_mov_b32 m0, s52
	s_nop 0
	global_load_lds_dwordx4 v[230:231], off
	s_waitcnt vmcnt(8)
	s_waitcnt lgkmcnt(0)
	s_setprio 1
	s_barrier
	v_mfma_f32_16x16x32_bf16 v[142:145], v[114:117], v[174:177], v[142:145]
	v_mfma_f32_16x16x32_bf16 v[142:145], v[118:121], v[178:181], v[142:145]
	v_mfma_f32_16x16x32_bf16 v[138:141], v[126:129], v[178:181], v[138:141]
	v_mfma_f32_16x16x32_bf16 v[138:141], v[122:125], v[174:177], v[138:141]
	v_mfma_f32_16x16x32_bf16 v[130:133], v[166:169], v[174:177], v[130:133]
	v_mfma_f32_16x16x32_bf16 v[130:133], v[170:173], v[178:181], v[130:133]
	v_mfma_f32_16x16x32_bf16 v[134:137], v[162:165], v[178:181], v[134:137]
	v_mfma_f32_16x16x32_bf16 v[134:137], v[158:161], v[174:177], v[134:137]
	v_mfma_f32_16x16x32_bf16 v[102:105], v[158:161], v[182:185], v[102:105]
	v_mfma_f32_16x16x32_bf16 v[102:105], v[162:165], v[186:189], v[102:105]
	v_mfma_f32_16x16x32_bf16 v[98:101], v[170:173], v[186:189], v[98:101]
	v_mfma_f32_16x16x32_bf16 v[98:101], v[166:169], v[182:185], v[98:101]
	v_mfma_f32_16x16x32_bf16 v[106:109], v[122:125], v[182:185], v[106:109]
	v_mfma_f32_16x16x32_bf16 v[106:109], v[126:129], v[186:189], v[106:109]
	v_mfma_f32_16x16x32_bf16 v[110:113], v[118:121], v[186:189], v[110:113]
	v_mfma_f32_16x16x32_bf16 v[110:113], v[114:117], v[182:185], v[110:113]
	v_mfma_f32_16x16x32_bf16 v[94:97], v[114:117], v[190:193], v[94:97]
	v_mfma_f32_16x16x32_bf16 v[94:97], v[118:121], v[202:205], v[94:97]
	v_mfma_f32_16x16x32_bf16 v[90:93], v[126:129], v[202:205], v[90:93]
	v_mfma_f32_16x16x32_bf16 v[90:93], v[122:125], v[190:193], v[90:93]
	v_mfma_f32_16x16x32_bf16 v[82:85], v[166:169], v[190:193], v[82:85]
	v_mfma_f32_16x16x32_bf16 v[82:85], v[170:173], v[202:205], v[82:85]
	v_mfma_f32_16x16x32_bf16 v[86:89], v[162:165], v[202:205], v[86:89]
	v_mfma_f32_16x16x32_bf16 v[86:89], v[158:161], v[190:193], v[86:89]
	v_mfma_f32_16x16x32_bf16 v[70:73], v[158:161], v[206:209], v[70:73]
	v_mfma_f32_16x16x32_bf16 v[70:73], v[162:165], v[210:213], v[70:73]
	v_mfma_f32_16x16x32_bf16 v[66:69], v[170:173], v[210:213], v[66:69]
	v_mfma_f32_16x16x32_bf16 v[66:69], v[166:169], v[206:209], v[66:69]
	v_mfma_f32_16x16x32_bf16 v[74:77], v[122:125], v[206:209], v[74:77]
	v_mfma_f32_16x16x32_bf16 v[74:77], v[126:129], v[210:213], v[74:77]
	v_mfma_f32_16x16x32_bf16 v[78:81], v[118:121], v[210:213], v[78:81]
	v_mfma_f32_16x16x32_bf16 v[78:81], v[114:117], v[206:209], v[78:81]
	s_barrier
	s_setprio 0
	s_add_i32 s36, s66, s48
	v_lshl_add_u64 v[154:155], v[154:155], 0, s[10:11]
	s_mov_b32 m0, s36
	ds_read_b128 v[174:177], v157 offset:49152
	ds_read_b128 v[178:181], v157 offset:50176
	ds_read_b128 v[182:185], v157 offset:51200
	ds_read_b128 v[186:189], v157 offset:52224
	ds_read_b128 v[190:193], v157 offset:53248
	ds_read_b128 v[202:205], v157 offset:54272
	ds_read_b128 v[206:209], v157 offset:55296
	ds_read_b128 v[210:213], v157 offset:56320
	global_load_lds_dwordx4 v[154:155], off
	s_add_i32 m0, s36, 0x2000
	s_add_u32 s30, s30, 0x80080
	v_lshl_add_u64 v[154:155], v[214:215], 0, s[10:11]
	s_addc_u32 s31, s31, 0
	s_add_i32 s36, s67, s48
	global_load_lds_dwordx4 v[154:155], off
	v_lshl_add_u64 v[154:155], s[30:31], 0, v[146:147]
	s_mov_b32 m0, s36
	s_nop 0
	global_load_lds_dwordx4 v[154:155], off
	v_lshl_add_u64 v[154:155], s[30:31], 0, v[148:149]
	s_add_i32 m0, s36, 0x2000
	s_nop 0
	global_load_lds_dwordx4 v[154:155], off
	v_lshl_add_u64 v[154:155], v[216:217], 0, s[10:11]
	s_mov_b32 m0, s53
	s_nop 0
	global_load_lds_dwordx4 v[154:155], off
	v_lshl_add_u64 v[154:155], v[228:229], 0, s[10:11]
	s_mov_b32 m0, s56
	s_nop 0
	global_load_lds_dwordx4 v[154:155], off
	s_waitcnt vmcnt(8)
	s_waitcnt lgkmcnt(0)
	s_setprio 1
	s_barrier
	v_mfma_f32_16x16x32_bf16 v[62:65], v[114:117], v[174:177], v[62:65]
	v_mfma_f32_16x16x32_bf16 v[62:65], v[118:121], v[178:181], v[62:65]
	v_mfma_f32_16x16x32_bf16 v[58:61], v[126:129], v[178:181], v[58:61]
	v_mfma_f32_16x16x32_bf16 v[58:61], v[122:125], v[174:177], v[58:61]
	v_mfma_f32_16x16x32_bf16 v[50:53], v[166:169], v[174:177], v[50:53]
	v_mfma_f32_16x16x32_bf16 v[50:53], v[170:173], v[178:181], v[50:53]
	v_mfma_f32_16x16x32_bf16 v[54:57], v[162:165], v[178:181], v[54:57]
	v_mfma_f32_16x16x32_bf16 v[54:57], v[158:161], v[174:177], v[54:57]
	v_mfma_f32_16x16x32_bf16 v[38:41], v[158:161], v[182:185], v[38:41]
	v_mfma_f32_16x16x32_bf16 v[38:41], v[162:165], v[186:189], v[38:41]
	v_mfma_f32_16x16x32_bf16 v[34:37], v[170:173], v[186:189], v[34:37]
	v_mfma_f32_16x16x32_bf16 v[34:37], v[166:169], v[182:185], v[34:37]
	v_mfma_f32_16x16x32_bf16 v[42:45], v[122:125], v[182:185], v[42:45]
	v_mfma_f32_16x16x32_bf16 v[42:45], v[126:129], v[186:189], v[42:45]
	v_mfma_f32_16x16x32_bf16 v[46:49], v[118:121], v[186:189], v[46:49]
	v_mfma_f32_16x16x32_bf16 v[46:49], v[114:117], v[182:185], v[46:49]
	v_mfma_f32_16x16x32_bf16 v[30:33], v[114:117], v[190:193], v[30:33]
	v_mfma_f32_16x16x32_bf16 v[30:33], v[118:121], v[202:205], v[30:33]
	v_mfma_f32_16x16x32_bf16 v[26:29], v[126:129], v[202:205], v[26:29]
	v_mfma_f32_16x16x32_bf16 v[26:29], v[122:125], v[190:193], v[26:29]
	v_mfma_f32_16x16x32_bf16 v[18:21], v[166:169], v[190:193], v[18:21]
	v_mfma_f32_16x16x32_bf16 v[18:21], v[170:173], v[202:205], v[18:21]
	v_mfma_f32_16x16x32_bf16 v[22:25], v[162:165], v[202:205], v[22:25]
	v_mfma_f32_16x16x32_bf16 v[22:25], v[158:161], v[190:193], v[22:25]
	v_mfma_f32_16x16x32_bf16 v[6:9], v[158:161], v[206:209], v[6:9]
	v_mfma_f32_16x16x32_bf16 v[6:9], v[162:165], v[210:213], v[6:9]
	v_mfma_f32_16x16x32_bf16 v[2:5], v[170:173], v[210:213], v[2:5]
	v_mfma_f32_16x16x32_bf16 v[2:5], v[166:169], v[206:209], v[2:5]
	v_mfma_f32_16x16x32_bf16 v[10:13], v[122:125], v[206:209], v[10:13]
	v_mfma_f32_16x16x32_bf16 v[10:13], v[126:129], v[210:213], v[10:13]
	v_mfma_f32_16x16x32_bf16 v[14:17], v[118:121], v[210:213], v[14:17]
	v_mfma_f32_16x16x32_bf16 v[14:17], v[114:117], v[206:209], v[14:17]
	s_barrier
	s_setprio 0
	s_add_i32 s65, s65, 2
	s_add_u32 s28, s28, 0x100
	s_addc_u32 s29, s29, 0
	s_add_u32 s63, s63, 0x100
	s_addc_u32 s64, s64, 0
	s_cmp_gt_u32 s65, 29
	s_cbranch_scc0 .LBB0_1272
	s_and_b64 vcc, exec, s[18:19]
	s_cbranch_vccz .LBB0_1275
	s_barrier

.LBB0_1346:
	s_or_b32 s20, s30, 1
	s_mul_hi_u32 s31, s20, 0x280000
	s_mul_i32 s42, s20, 0x280000
	s_add_u32 s20, s56, s18
	s_addc_u32 s21, s57, s19
	s_add_u32 s18, s16, 0x280000
	s_addc_u32 s19, s17, 0
	s_add_i32 s44, 0, 0x10000
	s_add_i32 s45, 0, 0x14000
	v_add_u32_e32 v146, s44, v44
	v_add_u32_e32 v162, s45, v44
	ds_read_b128 v[46:49], v146
	ds_read_b128 v[58:61], v146 offset:1024
	ds_read_b128 v[62:65], v146 offset:2048
	ds_read_b128 v[146:149], v146 offset:3072
	ds_read_b128 v[150:153], v162
	ds_read_b128 v[154:157], v162 offset:1024
	ds_read_b128 v[158:161], v162 offset:2048
	ds_read_b128 v[162:165], v162 offset:3072
	s_add_u32 s42, s62, s42
	s_addc_u32 s43, s63, s31
	v_lshl_add_u64 v[206:207], s[42:43], 0, v[194:195]
	s_add_i32 m0, s24, 0xc000
	ds_read_b128 v[166:169], v45
	ds_read_b128 v[170:173], v45 offset:1024
	ds_read_b128 v[174:177], v45 offset:2048
	ds_read_b128 v[178:181], v45 offset:3072
	ds_read_b128 v[182:185], v45 offset:4096
	ds_read_b128 v[186:189], v45 offset:5120
	ds_read_b128 v[190:193], v45 offset:6144
	ds_read_b128 v[202:205], v45 offset:7168
	global_load_lds_dwordx4 v[206:207], off
	v_lshl_add_u64 v[206:207], s[42:43], 0, v[42:43]
	s_add_i32 m0, s24, 0xe000
	s_nop 0
	global_load_lds_dwordx4 v[206:207], off
	s_waitcnt vmcnt(8)
	s_waitcnt lgkmcnt(0)
	s_setprio 1
	s_barrier
	v_mfma_f32_16x16x32_bf16 v[142:145], v[46:49], v[166:169], v[142:145]
	v_mfma_f32_16x16x32_bf16 v[142:145], v[58:61], v[170:173], v[142:145]
	v_mfma_f32_16x16x32_bf16 v[138:141], v[146:149], v[170:173], v[138:141]
	v_mfma_f32_16x16x32_bf16 v[138:141], v[62:65], v[166:169], v[138:141]
	v_mfma_f32_16x16x32_bf16 v[130:133], v[158:161], v[166:169], v[130:133]
	v_mfma_f32_16x16x32_bf16 v[130:133], v[162:165], v[170:173], v[130:133]
	v_mfma_f32_16x16x32_bf16 v[134:137], v[154:157], v[170:173], v[134:137]
	v_mfma_f32_16x16x32_bf16 v[134:137], v[150:153], v[166:169], v[134:137]
	v_mfma_f32_16x16x32_bf16 v[118:121], v[150:153], v[174:177], v[118:121]
	v_mfma_f32_16x16x32_bf16 v[118:121], v[154:157], v[178:181], v[118:121]
	v_mfma_f32_16x16x32_bf16 v[114:117], v[162:165], v[178:181], v[114:117]
	v_mfma_f32_16x16x32_bf16 v[114:117], v[158:161], v[174:177], v[114:117]
	v_mfma_f32_16x16x32_bf16 v[122:125], v[62:65], v[174:177], v[122:125]
	v_mfma_f32_16x16x32_bf16 v[122:125], v[146:149], v[178:181], v[122:125]
	v_mfma_f32_16x16x32_bf16 v[126:129], v[58:61], v[178:181], v[126:129]
	v_mfma_f32_16x16x32_bf16 v[126:129], v[46:49], v[174:177], v[126:129]
	v_mfma_f32_16x16x32_bf16 v[110:113], v[46:49], v[182:185], v[110:113]
	v_mfma_f32_16x16x32_bf16 v[110:113], v[58:61], v[186:189], v[110:113]
	v_mfma_f32_16x16x32_bf16 v[106:109], v[146:149], v[186:189], v[106:109]
	v_mfma_f32_16x16x32_bf16 v[106:109], v[62:65], v[182:185], v[106:109]
	v_mfma_f32_16x16x32_bf16 v[98:101], v[158:161], v[182:185], v[98:101]
	v_mfma_f32_16x16x32_bf16 v[98:101], v[162:165], v[186:189], v[98:101]
	v_mfma_f32_16x16x32_bf16 v[102:105], v[154:157], v[186:189], v[102:105]
	v_mfma_f32_16x16x32_bf16 v[102:105], v[150:153], v[182:185], v[102:105]
	v_mfma_f32_16x16x32_bf16 v[86:89], v[150:153], v[190:193], v[86:89]
	v_mfma_f32_16x16x32_bf16 v[86:89], v[154:157], v[202:205], v[86:89]
	v_mfma_f32_16x16x32_bf16 v[82:85], v[162:165], v[202:205], v[82:85]
	v_mfma_f32_16x16x32_bf16 v[82:85], v[158:161], v[190:193], v[82:85]
	v_mfma_f32_16x16x32_bf16 v[90:93], v[62:65], v[190:193], v[90:93]
	v_mfma_f32_16x16x32_bf16 v[90:93], v[146:149], v[202:205], v[90:93]
	v_mfma_f32_16x16x32_bf16 v[94:97], v[58:61], v[202:205], v[94:97]
	v_mfma_f32_16x16x32_bf16 v[94:97], v[46:49], v[190:193], v[94:97]
	s_barrier
	s_setprio 0
	s_add_i32 s31, s44, s23
	v_lshl_add_u64 v[206:207], s[20:21], 0, v[194:195]
	s_mov_b32 m0, s31
	ds_read_b128 v[166:169], v45 offset:16384
	ds_read_b128 v[170:173], v45 offset:17408
	ds_read_b128 v[174:177], v45 offset:18432
	ds_read_b128 v[178:181], v45 offset:19456
	ds_read_b128 v[182:185], v45 offset:20480
	ds_read_b128 v[186:189], v45 offset:21504
	ds_read_b128 v[190:193], v45 offset:22528
	ds_read_b128 v[202:205], v45 offset:23552
	global_load_lds_dwordx4 v[206:207], off
	s_add_i32 m0, s31, 0x2000
	s_add_u32 s42, s20, 0x4000
	v_lshl_add_u64 v[206:207], s[20:21], 0, v[42:43]
	s_addc_u32 s43, s21, 0
	s_add_i32 s31, s45, s23
	global_load_lds_dwordx4 v[206:207], off
	v_lshl_add_u64 v[206:207], s[42:43], 0, v[194:195]
	s_mov_b32 m0, s31
	s_nop 0
	global_load_lds_dwordx4 v[206:207], off
	v_lshl_add_u64 v[206:207], s[42:43], 0, v[42:43]
	s_add_i32 m0, s31, 0x2000
	s_nop 0
	global_load_lds_dwordx4 v[206:207], off
	v_lshl_add_u64 v[206:207], s[16:17], 0, v[194:195]
	s_mov_b32 m0, s24
	s_nop 0
	global_load_lds_dwordx4 v[206:207], off
	v_lshl_add_u64 v[206:207], s[16:17], 0, v[42:43]
	s_mov_b32 m0, s25
	s_nop 0
	global_load_lds_dwordx4 v[206:207], off
	s_waitcnt vmcnt(8)
	s_waitcnt lgkmcnt(0)
	s_setprio 1
	s_barrier
	v_mfma_f32_16x16x32_bf16 v[78:81], v[46:49], v[166:169], v[78:81]
	v_mfma_f32_16x16x32_bf16 v[78:81], v[58:61], v[170:173], v[78:81]
	v_mfma_f32_16x16x32_bf16 v[74:77], v[146:149], v[170:173], v[74:77]
	v_mfma_f32_16x16x32_bf16 v[74:77], v[62:65], v[166:169], v[74:77]
	v_mfma_f32_16x16x32_bf16 v[50:53], v[62:65], v[174:177], v[50:53]
	v_mfma_f32_16x16x32_bf16 v[50:53], v[146:149], v[178:181], v[50:53]
	v_mfma_f32_16x16x32_bf16 v[54:57], v[58:61], v[178:181], v[54:57]
	v_mfma_f32_16x16x32_bf16 v[54:57], v[46:49], v[174:177], v[54:57]
	v_mfma_f32_16x16x32_bf16 v[30:33], v[46:49], v[182:185], v[30:33]
	v_mfma_f32_16x16x32_bf16 v[30:33], v[58:61], v[186:189], v[30:33]
	v_mfma_f32_16x16x32_bf16 v[26:29], v[146:149], v[186:189], v[26:29]
	v_mfma_f32_16x16x32_bf16 v[26:29], v[62:65], v[182:185], v[26:29]
	v_mfma_f32_16x16x32_bf16 v[10:13], v[62:65], v[190:193], v[10:13]
	v_mfma_f32_16x16x32_bf16 v[10:13], v[146:149], v[202:205], v[10:13]
	v_mfma_f32_16x16x32_bf16 v[14:17], v[58:61], v[202:205], v[14:17]
	v_mfma_f32_16x16x32_bf16 v[14:17], v[46:49], v[190:193], v[14:17]
	v_mfma_f32_16x16x32_bf16 v[38:41], v[150:153], v[174:177], v[38:41]
	v_mfma_f32_16x16x32_bf16 v[34:37], v[158:161], v[174:177], v[34:37]
	v_mfma_f32_16x16x32_bf16 v[22:25], v[150:153], v[182:185], v[22:25]
	v_mfma_f32_16x16x32_bf16 v[18:21], v[158:161], v[182:185], v[18:21]
	v_mfma_f32_16x16x32_bf16 v[6:9], v[150:153], v[190:193], v[6:9]
	v_mfma_f32_16x16x32_bf16 v[2:5], v[158:161], v[190:193], v[2:5]
	v_mfma_f32_16x16x32_bf16 v[46:49], v[150:153], v[166:169], v[70:73]
	v_mfma_f32_16x16x32_bf16 v[58:61], v[158:161], v[166:169], v[66:69]
	v_mfma_f32_16x16x32_bf16 v[38:41], v[154:157], v[178:181], v[38:41]
	v_mfma_f32_16x16x32_bf16 v[34:37], v[162:165], v[178:181], v[34:37]
	v_mfma_f32_16x16x32_bf16 v[22:25], v[154:157], v[186:189], v[22:25]
	v_mfma_f32_16x16x32_bf16 v[18:21], v[162:165], v[186:189], v[18:21]
	v_mfma_f32_16x16x32_bf16 v[6:9], v[154:157], v[202:205], v[6:9]
	v_mfma_f32_16x16x32_bf16 v[2:5], v[162:165], v[202:205], v[2:5]
	v_mfma_f32_16x16x32_bf16 v[46:49], v[154:157], v[170:173], v[46:49]
	v_mfma_f32_16x16x32_bf16 v[58:61], v[162:165], v[170:173], v[58:61]
	s_barrier
	s_setprio 0
	s_add_i32 s31, 0, 0x18000
	s_add_i32 s42, 0, 0x1c000
	v_add_u32_e32 v146, s31, v44
	v_add_u32_e32 v162, s42, v44
	ds_read_b128 v[62:65], v146
	ds_read_b128 v[66:69], v146 offset:1024
	ds_read_b128 v[70:73], v146 offset:2048
	ds_read_b128 v[146:149], v146 offset:3072
	ds_read_b128 v[150:153], v162
	ds_read_b128 v[154:157], v162 offset:1024
	ds_read_b128 v[158:161], v162 offset:2048
	ds_read_b128 v[162:165], v162 offset:3072
	s_add_u32 s16, s16, 0x4000
	s_addc_u32 s17, s17, 0
	s_mov_b32 m0, s26
	v_lshl_add_u64 v[206:207], s[16:17], 0, v[194:195]
	ds_read_b128 v[166:169], v45 offset:32768
	ds_read_b128 v[170:173], v45 offset:33792
	ds_read_b128 v[174:177], v45 offset:34816
	ds_read_b128 v[178:181], v45 offset:35840
	ds_read_b128 v[182:185], v45 offset:36864
	ds_read_b128 v[186:189], v45 offset:37888
	ds_read_b128 v[190:193], v45 offset:38912
	ds_read_b128 v[202:205], v45 offset:39936
	global_load_lds_dwordx4 v[206:207], off
	v_lshl_add_u64 v[206:207], s[16:17], 0, v[42:43]
	s_mov_b32 m0, s27
	s_nop 0
	global_load_lds_dwordx4 v[206:207], off
	s_waitcnt vmcnt(8)
	s_waitcnt lgkmcnt(0)
	s_setprio 1
	s_barrier
	v_mfma_f32_16x16x32_bf16 v[142:145], v[62:65], v[166:169], v[142:145]
	v_mfma_f32_16x16x32_bf16 v[142:145], v[66:69], v[170:173], v[142:145]
	v_mfma_f32_16x16x32_bf16 v[138:141], v[146:149], v[170:173], v[138:141]
	v_mfma_f32_16x16x32_bf16 v[138:141], v[70:73], v[166:169], v[138:141]
	v_mfma_f32_16x16x32_bf16 v[130:133], v[158:161], v[166:169], v[130:133]
	v_mfma_f32_16x16x32_bf16 v[130:133], v[162:165], v[170:173], v[130:133]
	v_mfma_f32_16x16x32_bf16 v[134:137], v[154:157], v[170:173], v[134:137]
	v_mfma_f32_16x16x32_bf16 v[134:137], v[150:153], v[166:169], v[134:137]
	v_mfma_f32_16x16x32_bf16 v[118:121], v[150:153], v[174:177], v[118:121]
	v_mfma_f32_16x16x32_bf16 v[118:121], v[154:157], v[178:181], v[118:121]
	v_mfma_f32_16x16x32_bf16 v[114:117], v[162:165], v[178:181], v[114:117]
	v_mfma_f32_16x16x32_bf16 v[114:117], v[158:161], v[174:177], v[114:117]
	v_mfma_f32_16x16x32_bf16 v[122:125], v[70:73], v[174:177], v[122:125]
	v_mfma_f32_16x16x32_bf16 v[122:125], v[146:149], v[178:181], v[122:125]
	v_mfma_f32_16x16x32_bf16 v[126:129], v[66:69], v[178:181], v[126:129]
	v_mfma_f32_16x16x32_bf16 v[126:129], v[62:65], v[174:177], v[126:129]
	v_mfma_f32_16x16x32_bf16 v[110:113], v[62:65], v[182:185], v[110:113]
	v_mfma_f32_16x16x32_bf16 v[110:113], v[66:69], v[186:189], v[110:113]
	v_mfma_f32_16x16x32_bf16 v[106:109], v[146:149], v[186:189], v[106:109]
	v_mfma_f32_16x16x32_bf16 v[106:109], v[70:73], v[182:185], v[106:109]
	v_mfma_f32_16x16x32_bf16 v[98:101], v[158:161], v[182:185], v[98:101]
	v_mfma_f32_16x16x32_bf16 v[98:101], v[162:165], v[186:189], v[98:101]
	v_mfma_f32_16x16x32_bf16 v[102:105], v[154:157], v[186:189], v[102:105]
	v_mfma_f32_16x16x32_bf16 v[102:105], v[150:153], v[182:185], v[102:105]
	v_mfma_f32_16x16x32_bf16 v[86:89], v[150:153], v[190:193], v[86:89]
	v_mfma_f32_16x16x32_bf16 v[86:89], v[154:157], v[202:205], v[86:89]
	v_mfma_f32_16x16x32_bf16 v[82:85], v[162:165], v[202:205], v[82:85]
	v_mfma_f32_16x16x32_bf16 v[82:85], v[158:161], v[190:193], v[82:85]
	v_mfma_f32_16x16x32_bf16 v[90:93], v[70:73], v[190:193], v[90:93]
	v_mfma_f32_16x16x32_bf16 v[90:93], v[146:149], v[202:205], v[90:93]
	v_mfma_f32_16x16x32_bf16 v[94:97], v[66:69], v[202:205], v[94:97]
	v_mfma_f32_16x16x32_bf16 v[94:97], v[62:65], v[190:193], v[94:97]
	s_barrier
	s_setprio 0
	s_add_u32 s16, s20, 0x40000
	s_addc_u32 s17, s21, 0
	s_add_i32 s31, s31, s23
	v_lshl_add_u64 v[206:207], s[16:17], 0, v[194:195]
	s_mov_b32 m0, s31
	ds_read_b128 v[166:169], v45 offset:49152
	ds_read_b128 v[170:173], v45 offset:50176
	ds_read_b128 v[174:177], v45 offset:51200
	ds_read_b128 v[178:181], v45 offset:52224
	ds_read_b128 v[182:185], v45 offset:53248
	ds_read_b128 v[186:189], v45 offset:54272
	ds_read_b128 v[190:193], v45 offset:55296
	ds_read_b128 v[202:205], v45 offset:56320
	global_load_lds_dwordx4 v[206:207], off
	s_add_i32 m0, s31, 0x2000
	v_lshl_add_u64 v[206:207], s[16:17], 0, v[42:43]
	s_add_u32 s16, s20, 0x44000
	s_addc_u32 s17, s21, 0
	s_add_i32 s20, s42, s23
	global_load_lds_dwordx4 v[206:207], off
	v_lshl_add_u64 v[206:207], s[16:17], 0, v[194:195]
	s_mov_b32 m0, s20
	s_nop 0
	global_load_lds_dwordx4 v[206:207], off
	v_lshl_add_u64 v[206:207], s[16:17], 0, v[42:43]
	s_add_i32 m0, s20, 0x2000
	s_nop 0
	global_load_lds_dwordx4 v[206:207], off
	v_lshl_add_u64 v[206:207], s[18:19], 0, v[194:195]
	s_mov_b32 m0, s28
	s_nop 0
	global_load_lds_dwordx4 v[206:207], off
	v_lshl_add_u64 v[206:207], s[18:19], 0, v[42:43]
	s_mov_b32 m0, s29
	s_nop 0
	global_load_lds_dwordx4 v[206:207], off
	s_waitcnt vmcnt(8)
	s_waitcnt lgkmcnt(0)
	s_setprio 1
	s_barrier
	v_mfma_f32_16x16x32_bf16 v[78:81], v[62:65], v[166:169], v[78:81]
	v_mfma_f32_16x16x32_bf16 v[78:81], v[66:69], v[170:173], v[78:81]
	v_mfma_f32_16x16x32_bf16 v[74:77], v[146:149], v[170:173], v[74:77]
	v_mfma_f32_16x16x32_bf16 v[74:77], v[70:73], v[166:169], v[74:77]
	v_mfma_f32_16x16x32_bf16 v[50:53], v[70:73], v[174:177], v[50:53]
	v_mfma_f32_16x16x32_bf16 v[50:53], v[146:149], v[178:181], v[50:53]
	v_mfma_f32_16x16x32_bf16 v[54:57], v[66:69], v[178:181], v[54:57]
	v_mfma_f32_16x16x32_bf16 v[54:57], v[62:65], v[174:177], v[54:57]
	v_mfma_f32_16x16x32_bf16 v[30:33], v[62:65], v[182:185], v[30:33]
	v_mfma_f32_16x16x32_bf16 v[30:33], v[66:69], v[186:189], v[30:33]
	v_mfma_f32_16x16x32_bf16 v[26:29], v[146:149], v[186:189], v[26:29]
	v_mfma_f32_16x16x32_bf16 v[26:29], v[70:73], v[182:185], v[26:29]
	v_mfma_f32_16x16x32_bf16 v[10:13], v[70:73], v[190:193], v[10:13]
	v_mfma_f32_16x16x32_bf16 v[10:13], v[146:149], v[202:205], v[10:13]
	v_mfma_f32_16x16x32_bf16 v[14:17], v[66:69], v[202:205], v[14:17]
	v_mfma_f32_16x16x32_bf16 v[14:17], v[62:65], v[190:193], v[14:17]
	v_mfma_f32_16x16x32_bf16 v[46:49], v[150:153], v[166:169], v[46:49]
	v_mfma_f32_16x16x32_bf16 v[70:73], v[154:157], v[170:173], v[46:49]
	v_mfma_f32_16x16x32_bf16 v[46:49], v[158:161], v[166:169], v[58:61]
	v_mfma_f32_16x16x32_bf16 v[38:41], v[150:153], v[174:177], v[38:41]
	v_mfma_f32_16x16x32_bf16 v[34:37], v[158:161], v[174:177], v[34:37]
	v_mfma_f32_16x16x32_bf16 v[22:25], v[150:153], v[182:185], v[22:25]
	v_mfma_f32_16x16x32_bf16 v[18:21], v[158:161], v[182:185], v[18:21]
	v_mfma_f32_16x16x32_bf16 v[6:9], v[150:153], v[190:193], v[6:9]
	v_mfma_f32_16x16x32_bf16 v[2:5], v[158:161], v[190:193], v[2:5]
	v_mfma_f32_16x16x32_bf16 v[66:69], v[162:165], v[170:173], v[46:49]
	v_mfma_f32_16x16x32_bf16 v[38:41], v[154:157], v[178:181], v[38:41]
	v_mfma_f32_16x16x32_bf16 v[34:37], v[162:165], v[178:181], v[34:37]
	v_mfma_f32_16x16x32_bf16 v[22:25], v[154:157], v[186:189], v[22:25]
	v_mfma_f32_16x16x32_bf16 v[18:21], v[162:165], v[186:189], v[18:21]
	v_mfma_f32_16x16x32_bf16 v[6:9], v[154:157], v[202:205], v[6:9]
	v_mfma_f32_16x16x32_bf16 v[2:5], v[162:165], v[202:205], v[2:5]
	s_barrier
	s_setprio 0
	s_cmp_gt_u32 s30, 61
	s_mov_b32 s30, s4
	s_cbranch_scc1 .LBB0_1349

.LBB0_1502:
	s_or_b32 s82, s81, 1
	s_add_u32 vcc_lo, s26, vcc_lo
	s_addc_u32 vcc_hi, s27, vcc_hi
	s_and_b64 s[46:47], exec, s[46:47]
	s_cselect_b32 vcc_hi, s19, vcc_hi
	s_cselect_b32 vcc_lo, s21, vcc_lo
	s_add_u32 s46, s44, 0x280000
	s_addc_u32 s47, s45, 0
	s_add_i32 s88, 0, 0x10000
	s_add_i32 s89, 0, 0x14000
	v_add_u32_e32 v62, s88, v184
	v_add_u32_e32 v160, s89, v184
	ds_read_b128 v[50:53], v62
	ds_read_b128 v[54:57], v62 offset:1024
	ds_read_b128 v[58:61], v62 offset:2048
	ds_read_b128 v[62:65], v62 offset:3072
	ds_read_b128 v[146:149], v160
	ds_read_b128 v[150:153], v160 offset:1024
	ds_read_b128 v[156:159], v160 offset:2048
	ds_read_b128 v[160:163], v160 offset:3072
	s_mul_hi_u32 s83, s82, 0x280000
	s_mul_i32 s82, s82, 0x280000
	s_add_u32 s82, s79, s82
	s_addc_u32 s83, s80, s83
	v_lshl_add_u64 v[206:207], s[82:83], 0, v[194:195]
	s_add_i32 m0, s68, 0xc000
	ds_read_b128 v[164:167], v185
	ds_read_b128 v[168:171], v185 offset:1024
	ds_read_b128 v[172:175], v185 offset:2048
	ds_read_b128 v[176:179], v185 offset:3072
	ds_read_b128 v[180:183], v185 offset:4096
	ds_read_b128 v[186:189], v185 offset:5120
	ds_read_b128 v[190:193], v185 offset:6144
	ds_read_b128 v[202:205], v185 offset:7168
	global_load_lds_dwordx4 v[206:207], off
	v_lshl_add_u64 v[206:207], s[82:83], 0, v[154:155]
	s_add_i32 m0, s68, 0xe000
	s_nop 0
	global_load_lds_dwordx4 v[206:207], off
	s_waitcnt vmcnt(8)
	s_waitcnt lgkmcnt(0)
	s_setprio 1
	s_barrier
	v_mfma_f32_16x16x32_bf16 v[142:145], v[50:53], v[164:167], v[142:145]
	v_mfma_f32_16x16x32_bf16 v[142:145], v[54:57], v[168:171], v[142:145]
	v_mfma_f32_16x16x32_bf16 v[138:141], v[62:65], v[168:171], v[138:141]
	v_mfma_f32_16x16x32_bf16 v[138:141], v[58:61], v[164:167], v[138:141]
	v_mfma_f32_16x16x32_bf16 v[130:133], v[156:159], v[164:167], v[130:133]
	v_mfma_f32_16x16x32_bf16 v[130:133], v[160:163], v[168:171], v[130:133]
	v_mfma_f32_16x16x32_bf16 v[134:137], v[150:153], v[168:171], v[134:137]
	v_mfma_f32_16x16x32_bf16 v[134:137], v[146:149], v[164:167], v[134:137]
	v_mfma_f32_16x16x32_bf16 v[118:121], v[146:149], v[172:175], v[118:121]
	v_mfma_f32_16x16x32_bf16 v[118:121], v[150:153], v[176:179], v[118:121]
	v_mfma_f32_16x16x32_bf16 v[114:117], v[160:163], v[176:179], v[114:117]
	v_mfma_f32_16x16x32_bf16 v[114:117], v[156:159], v[172:175], v[114:117]
	v_mfma_f32_16x16x32_bf16 v[122:125], v[58:61], v[172:175], v[122:125]
	v_mfma_f32_16x16x32_bf16 v[122:125], v[62:65], v[176:179], v[122:125]
	v_mfma_f32_16x16x32_bf16 v[126:129], v[54:57], v[176:179], v[126:129]
	v_mfma_f32_16x16x32_bf16 v[126:129], v[50:53], v[172:175], v[126:129]
	v_mfma_f32_16x16x32_bf16 v[110:113], v[50:53], v[180:183], v[110:113]
	v_mfma_f32_16x16x32_bf16 v[110:113], v[54:57], v[186:189], v[110:113]
	v_mfma_f32_16x16x32_bf16 v[106:109], v[62:65], v[186:189], v[106:109]
	v_mfma_f32_16x16x32_bf16 v[106:109], v[58:61], v[180:183], v[106:109]
	v_mfma_f32_16x16x32_bf16 v[98:101], v[156:159], v[180:183], v[98:101]
	v_mfma_f32_16x16x32_bf16 v[98:101], v[160:163], v[186:189], v[98:101]
	v_mfma_f32_16x16x32_bf16 v[102:105], v[150:153], v[186:189], v[102:105]
	v_mfma_f32_16x16x32_bf16 v[102:105], v[146:149], v[180:183], v[102:105]
	v_mfma_f32_16x16x32_bf16 v[86:89], v[146:149], v[190:193], v[86:89]
	v_mfma_f32_16x16x32_bf16 v[86:89], v[150:153], v[202:205], v[86:89]
	v_mfma_f32_16x16x32_bf16 v[82:85], v[160:163], v[202:205], v[82:85]
	v_mfma_f32_16x16x32_bf16 v[82:85], v[156:159], v[190:193], v[82:85]
	v_mfma_f32_16x16x32_bf16 v[90:93], v[58:61], v[190:193], v[90:93]
	v_mfma_f32_16x16x32_bf16 v[90:93], v[62:65], v[202:205], v[90:93]
	v_mfma_f32_16x16x32_bf16 v[94:97], v[54:57], v[202:205], v[94:97]
	v_mfma_f32_16x16x32_bf16 v[94:97], v[50:53], v[190:193], v[94:97]
	s_barrier
	s_setprio 0
	s_add_i32 s82, s88, s67
	v_lshl_add_u64 v[206:207], vcc, 0, v[194:195]
	s_mov_b32 m0, s82
	ds_read_b128 v[164:167], v185 offset:16384
	ds_read_b128 v[168:171], v185 offset:17408
	ds_read_b128 v[172:175], v185 offset:18432
	ds_read_b128 v[176:179], v185 offset:19456
	ds_read_b128 v[180:183], v185 offset:20480
	ds_read_b128 v[186:189], v185 offset:21504
	ds_read_b128 v[190:193], v185 offset:22528
	ds_read_b128 v[202:205], v185 offset:23552
	global_load_lds_dwordx4 v[206:207], off
	s_add_i32 m0, s82, 0x2000
	s_add_u32 s82, vcc_lo, 0x4000
	v_lshl_add_u64 v[206:207], vcc, 0, v[154:155]
	s_addc_u32 s83, vcc_hi, 0
	s_add_i32 s88, s89, s67
	global_load_lds_dwordx4 v[206:207], off
	v_lshl_add_u64 v[206:207], s[82:83], 0, v[194:195]
	s_mov_b32 m0, s88
	s_nop 0
	global_load_lds_dwordx4 v[206:207], off
	v_lshl_add_u64 v[206:207], s[82:83], 0, v[154:155]
	s_add_i32 m0, s88, 0x2000
	s_nop 0
	global_load_lds_dwordx4 v[206:207], off
	v_lshl_add_u64 v[206:207], s[44:45], 0, v[194:195]
	s_mov_b32 m0, s68
	s_nop 0
	global_load_lds_dwordx4 v[206:207], off
	v_lshl_add_u64 v[206:207], s[44:45], 0, v[154:155]
	s_mov_b32 m0, s69
	s_nop 0
	global_load_lds_dwordx4 v[206:207], off
	s_waitcnt vmcnt(8)
	s_waitcnt lgkmcnt(0)
	s_setprio 1
	s_barrier
	v_mfma_f32_16x16x32_bf16 v[78:81], v[50:53], v[164:167], v[78:81]
	v_mfma_f32_16x16x32_bf16 v[78:81], v[54:57], v[168:171], v[78:81]
	v_mfma_f32_16x16x32_bf16 v[74:77], v[62:65], v[168:171], v[74:77]
	v_mfma_f32_16x16x32_bf16 v[74:77], v[58:61], v[164:167], v[74:77]
	v_mfma_f32_16x16x32_bf16 v[42:45], v[58:61], v[172:175], v[42:45]
	v_mfma_f32_16x16x32_bf16 v[42:45], v[62:65], v[176:179], v[42:45]
	v_mfma_f32_16x16x32_bf16 v[46:49], v[54:57], v[176:179], v[46:49]
	v_mfma_f32_16x16x32_bf16 v[46:49], v[50:53], v[172:175], v[46:49]
	v_mfma_f32_16x16x32_bf16 v[30:33], v[50:53], v[180:183], v[30:33]
	v_mfma_f32_16x16x32_bf16 v[30:33], v[54:57], v[186:189], v[30:33]
	v_mfma_f32_16x16x32_bf16 v[26:29], v[62:65], v[186:189], v[26:29]
	v_mfma_f32_16x16x32_bf16 v[26:29], v[58:61], v[180:183], v[26:29]
	v_mfma_f32_16x16x32_bf16 v[10:13], v[58:61], v[190:193], v[10:13]
	v_mfma_f32_16x16x32_bf16 v[10:13], v[62:65], v[202:205], v[10:13]
	v_mfma_f32_16x16x32_bf16 v[14:17], v[54:57], v[202:205], v[14:17]
	v_mfma_f32_16x16x32_bf16 v[14:17], v[50:53], v[190:193], v[14:17]
	v_mfma_f32_16x16x32_bf16 v[38:41], v[146:149], v[172:175], v[38:41]
	v_mfma_f32_16x16x32_bf16 v[34:37], v[156:159], v[172:175], v[34:37]
	v_mfma_f32_16x16x32_bf16 v[22:25], v[146:149], v[180:183], v[22:25]
	v_mfma_f32_16x16x32_bf16 v[18:21], v[156:159], v[180:183], v[18:21]
	v_mfma_f32_16x16x32_bf16 v[6:9], v[146:149], v[190:193], v[6:9]
	v_mfma_f32_16x16x32_bf16 v[2:5], v[156:159], v[190:193], v[2:5]
	v_mfma_f32_16x16x32_bf16 v[50:53], v[146:149], v[164:167], v[70:73]
	v_mfma_f32_16x16x32_bf16 v[54:57], v[156:159], v[164:167], v[66:69]
	v_mfma_f32_16x16x32_bf16 v[38:41], v[150:153], v[176:179], v[38:41]
	v_mfma_f32_16x16x32_bf16 v[34:37], v[160:163], v[176:179], v[34:37]
	v_mfma_f32_16x16x32_bf16 v[22:25], v[150:153], v[186:189], v[22:25]
	v_mfma_f32_16x16x32_bf16 v[18:21], v[160:163], v[186:189], v[18:21]
	v_mfma_f32_16x16x32_bf16 v[6:9], v[150:153], v[202:205], v[6:9]
	v_mfma_f32_16x16x32_bf16 v[2:5], v[160:163], v[202:205], v[2:5]
	v_mfma_f32_16x16x32_bf16 v[50:53], v[150:153], v[168:171], v[50:53]
	v_mfma_f32_16x16x32_bf16 v[54:57], v[160:163], v[168:171], v[54:57]
	s_barrier
	s_setprio 0
	s_add_i32 s82, 0, 0x18000
	s_add_i32 s83, 0, 0x1c000
	v_add_u32_e32 v70, s82, v184
	v_add_u32_e32 v160, s83, v184
	ds_read_b128 v[58:61], v70
	ds_read_b128 v[62:65], v70 offset:1024
	ds_read_b128 v[66:69], v70 offset:2048
	ds_read_b128 v[70:73], v70 offset:3072
	ds_read_b128 v[146:149], v160
	ds_read_b128 v[150:153], v160 offset:1024
	ds_read_b128 v[156:159], v160 offset:2048
	ds_read_b128 v[160:163], v160 offset:3072
	s_add_u32 s44, s44, 0x4000
	s_addc_u32 s45, s45, 0
	s_mov_b32 m0, s72
	v_lshl_add_u64 v[206:207], s[44:45], 0, v[194:195]
	ds_read_b128 v[164:167], v185 offset:32768
	ds_read_b128 v[168:171], v185 offset:33792
	ds_read_b128 v[172:175], v185 offset:34816
	ds_read_b128 v[176:179], v185 offset:35840
	ds_read_b128 v[180:183], v185 offset:36864
	ds_read_b128 v[186:189], v185 offset:37888
	ds_read_b128 v[190:193], v185 offset:38912
	ds_read_b128 v[202:205], v185 offset:39936
	global_load_lds_dwordx4 v[206:207], off
	v_lshl_add_u64 v[206:207], s[44:45], 0, v[154:155]
	s_mov_b32 m0, s73
	s_nop 0
	global_load_lds_dwordx4 v[206:207], off
	s_waitcnt vmcnt(8)
	s_waitcnt lgkmcnt(0)
	s_setprio 1
	s_barrier
	v_mfma_f32_16x16x32_bf16 v[142:145], v[58:61], v[164:167], v[142:145]
	v_mfma_f32_16x16x32_bf16 v[142:145], v[62:65], v[168:171], v[142:145]
	v_mfma_f32_16x16x32_bf16 v[138:141], v[70:73], v[168:171], v[138:141]
	v_mfma_f32_16x16x32_bf16 v[138:141], v[66:69], v[164:167], v[138:141]
	v_mfma_f32_16x16x32_bf16 v[130:133], v[156:159], v[164:167], v[130:133]
	v_mfma_f32_16x16x32_bf16 v[130:133], v[160:163], v[168:171], v[130:133]
	v_mfma_f32_16x16x32_bf16 v[134:137], v[150:153], v[168:171], v[134:137]
	v_mfma_f32_16x16x32_bf16 v[134:137], v[146:149], v[164:167], v[134:137]
	v_mfma_f32_16x16x32_bf16 v[118:121], v[146:149], v[172:175], v[118:121]
	v_mfma_f32_16x16x32_bf16 v[118:121], v[150:153], v[176:179], v[118:121]
	v_mfma_f32_16x16x32_bf16 v[114:117], v[160:163], v[176:179], v[114:117]
	v_mfma_f32_16x16x32_bf16 v[114:117], v[156:159], v[172:175], v[114:117]
	v_mfma_f32_16x16x32_bf16 v[122:125], v[66:69], v[172:175], v[122:125]
	v_mfma_f32_16x16x32_bf16 v[122:125], v[70:73], v[176:179], v[122:125]
	v_mfma_f32_16x16x32_bf16 v[126:129], v[62:65], v[176:179], v[126:129]
	v_mfma_f32_16x16x32_bf16 v[126:129], v[58:61], v[172:175], v[126:129]
	v_mfma_f32_16x16x32_bf16 v[110:113], v[58:61], v[180:183], v[110:113]
	v_mfma_f32_16x16x32_bf16 v[110:113], v[62:65], v[186:189], v[110:113]
	v_mfma_f32_16x16x32_bf16 v[106:109], v[70:73], v[186:189], v[106:109]
	v_mfma_f32_16x16x32_bf16 v[106:109], v[66:69], v[180:183], v[106:109]
	v_mfma_f32_16x16x32_bf16 v[98:101], v[156:159], v[180:183], v[98:101]
	v_mfma_f32_16x16x32_bf16 v[98:101], v[160:163], v[186:189], v[98:101]
	v_mfma_f32_16x16x32_bf16 v[102:105], v[150:153], v[186:189], v[102:105]
	v_mfma_f32_16x16x32_bf16 v[102:105], v[146:149], v[180:183], v[102:105]
	v_mfma_f32_16x16x32_bf16 v[86:89], v[146:149], v[190:193], v[86:89]
	v_mfma_f32_16x16x32_bf16 v[86:89], v[150:153], v[202:205], v[86:89]
	v_mfma_f32_16x16x32_bf16 v[82:85], v[160:163], v[202:205], v[82:85]
	v_mfma_f32_16x16x32_bf16 v[82:85], v[156:159], v[190:193], v[82:85]
	v_mfma_f32_16x16x32_bf16 v[90:93], v[66:69], v[190:193], v[90:93]
	v_mfma_f32_16x16x32_bf16 v[90:93], v[70:73], v[202:205], v[90:93]
	v_mfma_f32_16x16x32_bf16 v[94:97], v[62:65], v[202:205], v[94:97]
	v_mfma_f32_16x16x32_bf16 v[94:97], v[58:61], v[190:193], v[94:97]
	s_barrier
	s_setprio 0
	s_add_u32 s44, vcc_lo, 0x40000
	s_addc_u32 s45, vcc_hi, 0
	s_add_i32 s82, s82, s67
	v_lshl_add_u64 v[206:207], s[44:45], 0, v[194:195]
	s_mov_b32 m0, s82
	ds_read_b128 v[164:167], v185 offset:49152
	ds_read_b128 v[168:171], v185 offset:50176
	ds_read_b128 v[172:175], v185 offset:51200
	ds_read_b128 v[176:179], v185 offset:52224
	ds_read_b128 v[180:183], v185 offset:53248
	ds_read_b128 v[186:189], v185 offset:54272
	ds_read_b128 v[190:193], v185 offset:55296
	ds_read_b128 v[202:205], v185 offset:56320
	global_load_lds_dwordx4 v[206:207], off
	s_add_i32 m0, s82, 0x2000
	v_lshl_add_u64 v[206:207], s[44:45], 0, v[154:155]
	s_add_u32 s44, vcc_lo, 0x44000
	s_addc_u32 s45, vcc_hi, 0
	s_add_i32 s82, s83, s67
	global_load_lds_dwordx4 v[206:207], off
	v_lshl_add_u64 v[206:207], s[44:45], 0, v[194:195]
	s_mov_b32 m0, s82
	s_nop 0
	global_load_lds_dwordx4 v[206:207], off
	v_lshl_add_u64 v[206:207], s[44:45], 0, v[154:155]
	s_add_i32 m0, s82, 0x2000
	s_nop 0
	global_load_lds_dwordx4 v[206:207], off
	v_lshl_add_u64 v[206:207], s[46:47], 0, v[194:195]
	s_mov_b32 m0, s76
	s_nop 0
	global_load_lds_dwordx4 v[206:207], off
	v_lshl_add_u64 v[206:207], s[46:47], 0, v[154:155]
	s_mov_b32 m0, s77
	s_nop 0
	global_load_lds_dwordx4 v[206:207], off
	s_waitcnt vmcnt(8)
	s_waitcnt lgkmcnt(0)
	s_setprio 1
	s_barrier
	v_mfma_f32_16x16x32_bf16 v[78:81], v[58:61], v[164:167], v[78:81]
	v_mfma_f32_16x16x32_bf16 v[78:81], v[62:65], v[168:171], v[78:81]
	v_mfma_f32_16x16x32_bf16 v[74:77], v[70:73], v[168:171], v[74:77]
	v_mfma_f32_16x16x32_bf16 v[74:77], v[66:69], v[164:167], v[74:77]
	v_mfma_f32_16x16x32_bf16 v[42:45], v[66:69], v[172:175], v[42:45]
	v_mfma_f32_16x16x32_bf16 v[42:45], v[70:73], v[176:179], v[42:45]
	v_mfma_f32_16x16x32_bf16 v[46:49], v[62:65], v[176:179], v[46:49]
	v_mfma_f32_16x16x32_bf16 v[46:49], v[58:61], v[172:175], v[46:49]
	v_mfma_f32_16x16x32_bf16 v[30:33], v[58:61], v[180:183], v[30:33]
	v_mfma_f32_16x16x32_bf16 v[30:33], v[62:65], v[186:189], v[30:33]
	v_mfma_f32_16x16x32_bf16 v[26:29], v[70:73], v[186:189], v[26:29]
	v_mfma_f32_16x16x32_bf16 v[26:29], v[66:69], v[180:183], v[26:29]
	v_mfma_f32_16x16x32_bf16 v[10:13], v[66:69], v[190:193], v[10:13]
	v_mfma_f32_16x16x32_bf16 v[10:13], v[70:73], v[202:205], v[10:13]
	v_mfma_f32_16x16x32_bf16 v[14:17], v[62:65], v[202:205], v[14:17]
	v_mfma_f32_16x16x32_bf16 v[14:17], v[58:61], v[190:193], v[14:17]
	v_mfma_f32_16x16x32_bf16 v[50:53], v[146:149], v[164:167], v[50:53]
	v_mfma_f32_16x16x32_bf16 v[70:73], v[150:153], v[168:171], v[50:53]
	v_mfma_f32_16x16x32_bf16 v[50:53], v[156:159], v[164:167], v[54:57]
	v_mfma_f32_16x16x32_bf16 v[38:41], v[146:149], v[172:175], v[38:41]
	v_mfma_f32_16x16x32_bf16 v[34:37], v[156:159], v[172:175], v[34:37]
	v_mfma_f32_16x16x32_bf16 v[22:25], v[146:149], v[180:183], v[22:25]
	v_mfma_f32_16x16x32_bf16 v[18:21], v[156:159], v[180:183], v[18:21]
	v_mfma_f32_16x16x32_bf16 v[6:9], v[146:149], v[190:193], v[6:9]
	v_mfma_f32_16x16x32_bf16 v[2:5], v[156:159], v[190:193], v[2:5]
	v_mfma_f32_16x16x32_bf16 v[66:69], v[160:163], v[168:171], v[50:53]
	v_mfma_f32_16x16x32_bf16 v[38:41], v[150:153], v[176:179], v[38:41]
	v_mfma_f32_16x16x32_bf16 v[34:37], v[160:163], v[176:179], v[34:37]
	v_mfma_f32_16x16x32_bf16 v[22:25], v[150:153], v[186:189], v[22:25]
	v_mfma_f32_16x16x32_bf16 v[18:21], v[160:163], v[186:189], v[18:21]
	v_mfma_f32_16x16x32_bf16 v[6:9], v[150:153], v[202:205], v[6:9]
	v_mfma_f32_16x16x32_bf16 v[2:5], v[160:163], v[202:205], v[2:5]
	s_barrier
	s_setprio 0
	s_cmpk_gt_u32 s81, 0x7d
	s_mov_b32 s81, s4
	s_cbranch_scc1 .LBB0_1505
